# K-loop DMA waits split: first-phase stage pair now retired one K-tile later (vmcnt(8) in both load segments) for a full K-tile of flight time
# speedup vs baseline: 1.0006x; 1.0006x over previous
; #define PG8_STAGE(bufoff, gbase, voff) do { _Pragma("unroll") for (int _i = 0; _i < 2; ++_i) \
;         __builtin_amdgcn_global_load_lds((const unsigned*)((const char*)(gbase) + (voff)[_i]), (LAS unsigned*)(lds + (bufoff) + ldsw + _i * 8192), 16, 0, 0); } while (0)
; #define PG8_LDA(dst, b, h) do { _Pragma("unroll") for (int m = 0; m < 4; ++m) _Pragma("unroll") for (int k = 0; k < 2; ++k) dst[m][k] = *(const LAS bf16x8*)(lds + PG8_SA(b, h) + aoff + m * 2048 + k * 1024); } while (0)
; #define PG8_LDB(dst, b, h) do { _Pragma("unroll") for (int n = 0; n < 2; ++n) _Pragma("unroll") for (int k = 0; k < 2; ++k) dst[n][k] = *(const LAS bf16x8*)(lds + PG8_SB(b, h) + boff + n * 2048 + k * 1024); } while (0)
; #define PG8_WAIT_V(n) asm volatile("s_waitcnt vmcnt(" #n ")" ::: "memory")
; #define PG8_WAIT_L(n) asm volatile("s_waitcnt lgkmcnt(" #n ")" ::: "memory")
; #define PG8_BAR __builtin_amdgcn_s_barrier()
; #define PG8_SCHED __builtin_amdgcn_sched_barrier(0)
; template <class Epi>
; __device__ __forceinline__ void gemm_phase(LAS unsigned char* lds, const Gemm g, const StaticOrder& S, const Epi& E) {
;     ...
;         const bool has_next = S.next(ui + 1, nxt);
;         const char* nA = has_next ? (const char*)g.A + (size_t)nxt.pm * tstepA : cA; const char* nB = has_next ? (const char*)g.Bt + (size_t)nxt.pn * tstepB : cB;
;         for (int t = 0; t < nt; t += 2) {
;             const bool last = (t == nt - 2);
;             const char* a1 = cA + (size_t)(t + 1) * kstep;
;             const char* a2 = last ? nA : cA + (size_t)(t + 2) * kstep; const char* b2 = last ? nB : cB + (size_t)(t + 2) * kstep;
;             const char* a3 = a2 + kstep; const char* b3 = b2 + kstep;
;             PG8_LDB(B0, 0, 0); PG8_SCHED; PG8_LDA(At, 0, 0); PG8_STAGE(PG8_SA(1, 1), a1 + hstepA, voffA);
;             PG8_WAIT_L(8); PG8_BAR; PG8_WAIT_L(0); PG8_MMA(0, 0, At, B0); PG8_BAR; PG8_SCHED;
;             PG8_LDB(B1, 0, 1); PG8_STAGE(PG8_SB(0, 0), b2, voffB);
;             PG8_BAR; PG8_WAIT_L(0); PG8_MMA(0, 1, At, B1); PG8_BAR;
;             PG8_LDA(At, 0, 1); PG8_STAGE(PG8_SA(0, 0), a2, voffA);
;             PG8_BAR; PG8_WAIT_L(0); PG8_MMA(1, 0, At, B0); PG8_BAR; PG8_SCHED;
;             PG8_STAGE(PG8_SB(0, 1), b2 + hstepB, voffB);
;             PG8_WAIT_V(6); PG8_BAR; PG8_MMA(1, 1, At, B1); PG8_BAR;
.LBB0_140:
	v_mov_b64_e32 v[0:1], 0x800
	s_ashr_i32 s15, s14, 31
	v_cmp_lt_i64_e32 vcc, s[16:17], v[0:1]
	s_lshl_b64 s[16:17], s[14:15], 20
	v_readlane_b32 s18, v252, 53
	v_readlane_b32 s19, v252, 54
	s_add_u32 s16, s18, s16
	s_addc_u32 s17, s19, s17
	s_and_b64 s[18:19], vcc, exec
	s_cselect_b32 s15, s17, s23
	s_cselect_b32 s49, s16, s22
	s_ashr_i32 s5, s4, 31
	s_lshl_b64 s[18:19], s[4:5], 20
	s_add_u32 s18, s34, s18
	s_addc_u32 s19, s35, s19
	s_and_b64 s[26:27], vcc, exec
	s_cselect_b32 s5, s19, s25
	s_cselect_b32 s50, s18, s24
	s_add_u32 s22, s22, 0x84000
	s_addc_u32 s23, s23, 0
	s_add_u32 s51, s24, 0x8000
	s_addc_u32 s52, s25, 0
	s_mov_b32 s54, -2
	s_add_u32 s24, s22, 0xfff84000
	s_addc_u32 s25, s23, -1
	s_cmp_eq_u32 s54, 28
	s_cselect_b32 s28, s49, s24
	s_cselect_b32 s29, s15, s25
	s_cselect_b32 s24, s50, s51
	s_cselect_b32 s25, s5, s52
	s_add_u32 s26, s28, 0x4000
	s_addc_u32 s27, s29, 0
	s_add_i32 m0, s37, 0xc000
	v_lshl_add_u64 v[188:189], s[22:23], 0, v[128:129]
	global_load_lds_dwordx4 v[188:189], off
	s_add_i32 m0, s37, 0xe000
	v_lshl_add_u64 v[188:189], s[22:23], 0, v[130:131]
	global_load_lds_dwordx4 v[188:189], off
	s_mov_b32 s55, 0x10000
	v_add_u32_e32 v148, s55, v134
	ds_read_b128 v[136:139], v148
	ds_read_b128 v[144:147], v148 offset:2048
	ds_read_b128 v[140:143], v148 offset:1024
	ds_read_b128 v[148:151], v148 offset:3072
	ds_read_b128 v[156:159], v135
	ds_read_b128 v[164:167], v135 offset:2048
	ds_read_b128 v[172:175], v135 offset:4096
	ds_read_b128 v[180:183], v135 offset:6144
	ds_read_b128 v[160:163], v135 offset:1024
	ds_read_b128 v[168:171], v135 offset:3072
	ds_read_b128 v[176:179], v135 offset:5120
	ds_read_b128 v[184:187], v135 offset:7168
	s_mov_b32 s58, 0x14000
	s_add_i32 s55, s55, s36
	v_add_u32_e32 v152, s58, v134
	ds_read_b128 v[188:191], v152
	ds_read_b128 v[196:199], v152 offset:2048
	ds_read_b128 v[192:195], v152 offset:1024
	ds_read_b128 v[200:203], v152 offset:3072
	s_waitcnt vmcnt(8)
	s_waitcnt lgkmcnt(0)
	s_barrier
	v_mfma_f32_16x16x32_bf16 v[124:127], v[136:139], v[156:159], 0
	s_setprio 1
	v_mfma_f32_16x16x32_bf16 v[120:123], v[144:147], v[156:159], 0
	v_mfma_f32_16x16x32_bf16 v[108:111], v[136:139], v[164:167], 0
	v_mfma_f32_16x16x32_bf16 v[104:107], v[144:147], v[164:167], 0
	v_mfma_f32_16x16x32_bf16 v[92:95], v[136:139], v[172:175], 0
	v_mfma_f32_16x16x32_bf16 v[88:91], v[144:147], v[172:175], 0
	v_mfma_f32_16x16x32_bf16 v[76:79], v[136:139], v[180:183], 0
	v_mfma_f32_16x16x32_bf16 v[72:75], v[144:147], v[180:183], 0
	v_mfma_f32_16x16x32_bf16 v[124:127], v[140:143], v[160:163], v[124:127]
	v_mfma_f32_16x16x32_bf16 v[120:123], v[148:151], v[160:163], v[120:123]
	v_mfma_f32_16x16x32_bf16 v[108:111], v[140:143], v[168:171], v[108:111]
	v_mfma_f32_16x16x32_bf16 v[104:107], v[148:151], v[168:171], v[104:107]
	v_mfma_f32_16x16x32_bf16 v[92:95], v[140:143], v[176:179], v[92:95]
	v_mfma_f32_16x16x32_bf16 v[88:91], v[148:151], v[176:179], v[88:91]
	v_mfma_f32_16x16x32_bf16 v[76:79], v[140:143], v[184:187], v[76:79]
	v_mfma_f32_16x16x32_bf16 v[72:75], v[148:151], v[184:187], v[72:75]
	v_mfma_f32_16x16x32_bf16 v[116:119], v[188:191], v[156:159], 0
	v_mfma_f32_16x16x32_bf16 v[112:115], v[196:199], v[156:159], 0
	v_mfma_f32_16x16x32_bf16 v[100:103], v[188:191], v[164:167], 0
	v_mfma_f32_16x16x32_bf16 v[96:99], v[196:199], v[164:167], 0
	v_mfma_f32_16x16x32_bf16 v[84:87], v[188:191], v[172:175], 0
	v_mfma_f32_16x16x32_bf16 v[80:83], v[196:199], v[172:175], 0
	v_mfma_f32_16x16x32_bf16 v[68:71], v[188:191], v[180:183], 0
	v_mfma_f32_16x16x32_bf16 v[64:67], v[196:199], v[180:183], 0
	v_mfma_f32_16x16x32_bf16 v[116:119], v[192:195], v[160:163], v[116:119]
	v_mfma_f32_16x16x32_bf16 v[112:115], v[200:203], v[160:163], v[112:115]
	v_mfma_f32_16x16x32_bf16 v[100:103], v[192:195], v[168:171], v[100:103]
	v_mfma_f32_16x16x32_bf16 v[96:99], v[200:203], v[168:171], v[96:99]
	v_mfma_f32_16x16x32_bf16 v[84:87], v[192:195], v[176:179], v[84:87]
	v_mfma_f32_16x16x32_bf16 v[80:83], v[200:203], v[176:179], v[80:83]
	v_mfma_f32_16x16x32_bf16 v[68:71], v[192:195], v[184:187], v[68:71]
	s_setprio 0
	v_mfma_f32_16x16x32_bf16 v[64:67], v[200:203], v[184:187], v[64:67]
	s_barrier
	s_mov_b32 m0, s55
	v_lshl_add_u64 v[204:205], s[24:25], 0, v[128:129]
	global_load_lds_dwordx4 v[204:205], off
	s_add_i32 m0, s55, 0x2000
	v_lshl_add_u64 v[204:205], s[24:25], 0, v[130:131]
	global_load_lds_dwordx4 v[204:205], off
	s_mov_b32 m0, s37
	v_lshl_add_u64 v[204:205], s[28:29], 0, v[128:129]
	global_load_lds_dwordx4 v[204:205], off
	s_mov_b32 m0, s38
	v_lshl_add_u64 v[204:205], s[28:29], 0, v[130:131]
	global_load_lds_dwordx4 v[204:205], off
	s_add_u32 s56, s24, 0x80000
	s_addc_u32 s57, s25, 0
	s_add_i32 s55, s58, s36
	s_mov_b32 m0, s55
	v_lshl_add_u64 v[204:205], s[56:57], 0, v[128:129]
	global_load_lds_dwordx4 v[204:205], off
	s_add_i32 m0, s55, 0x2000
	v_lshl_add_u64 v[204:205], s[56:57], 0, v[130:131]
	global_load_lds_dwordx4 v[204:205], off
	ds_read_b128 v[156:159], v135 offset:16384
	ds_read_b128 v[164:167], v135 offset:18432
	ds_read_b128 v[172:175], v135 offset:20480
	ds_read_b128 v[180:183], v135 offset:22528
	ds_read_b128 v[160:163], v135 offset:17408
	ds_read_b128 v[168:171], v135 offset:19456
	ds_read_b128 v[176:179], v135 offset:21504
	ds_read_b128 v[184:187], v135 offset:23552
	s_waitcnt vmcnt(8)
	s_waitcnt lgkmcnt(0)
	s_barrier
; #define PG8_STAGE(bufoff, gbase, voff) do { _Pragma("unroll") for (int _i = 0; _i < 2; ++_i) \
;         __builtin_amdgcn_global_load_lds((const unsigned*)((const char*)(gbase) + (voff)[_i]), (LAS unsigned*)(lds + (bufoff) + ldsw + _i * 8192), 16, 0, 0); } while (0)
; #define PG8_LDA(dst, b, h) do { _Pragma("unroll") for (int m = 0; m < 4; ++m) _Pragma("unroll") for (int k = 0; k < 2; ++k) dst[m][k] = *(const LAS bf16x8*)(lds + PG8_SA(b, h) + aoff + m * 2048 + k * 1024); } while (0)
; #define PG8_LDB(dst, b, h) do { _Pragma("unroll") for (int n = 0; n < 2; ++n) _Pragma("unroll") for (int k = 0; k < 2; ++k) dst[n][k] = *(const LAS bf16x8*)(lds + PG8_SB(b, h) + boff + n * 2048 + k * 1024); } while (0)
; #define PG8_WAIT_V(n) asm volatile("s_waitcnt vmcnt(" #n ")" ::: "memory")
; #define PG8_WAIT_L(n) asm volatile("s_waitcnt lgkmcnt(" #n ")" ::: "memory")
; #define PG8_BAR __builtin_amdgcn_s_barrier()
; #define PG8_SCHED __builtin_amdgcn_sched_barrier(0)
; template <class Epi>
; __device__ __forceinline__ void gemm_phase(LAS unsigned char* lds, const Gemm g, const StaticOrder& S, const Epi& E) {
;     ...
;             PG8_LDB(B0, 0, 0); PG8_SCHED; PG8_LDA(At, 0, 0); PG8_STAGE(PG8_SA(1, 1), a1 + hstepA, voffA);
;             PG8_WAIT_L(8); PG8_BAR; PG8_WAIT_L(0); PG8_MMA(0, 0, At, B0); PG8_BAR; PG8_SCHED;
;             PG8_LDB(B1, 0, 1); PG8_STAGE(PG8_SB(0, 0), b2, voffB);
;             PG8_BAR; PG8_WAIT_L(0); PG8_MMA(0, 1, At, B1); PG8_BAR;
;             PG8_LDA(At, 0, 1); PG8_STAGE(PG8_SA(0, 0), a2, voffA);
;             PG8_BAR; PG8_WAIT_L(0); PG8_MMA(1, 0, At, B0); PG8_BAR; PG8_SCHED;
;             PG8_STAGE(PG8_SB(0, 1), b2 + hstepB, voffB);
;             PG8_WAIT_V(6); PG8_BAR; PG8_MMA(1, 1, At, B1); PG8_BAR;
;             PG8_LDB(B0, 1, 0); PG8_SCHED; PG8_LDA(At, 1, 0); PG8_STAGE(PG8_SA(0, 1), a2 + hstepA, voffA);
;             PG8_WAIT_L(8); PG8_BAR; PG8_WAIT_L(0); PG8_MMA(0, 0, At, B0); PG8_BAR; PG8_SCHED;
;             PG8_LDB(B1, 1, 1); PG8_STAGE(PG8_SB(1, 0), b3, voffB);
;             PG8_BAR; PG8_WAIT_L(0); PG8_MMA(0, 1, At, B1); PG8_BAR;
;             PG8_LDA(At, 1, 1); PG8_STAGE(PG8_SA(1, 0), a3, voffA);
;             PG8_BAR; PG8_WAIT_L(0); PG8_MMA(1, 0, At, B0); PG8_BAR; PG8_SCHED;
;             PG8_STAGE(PG8_SB(1, 1), b3 + hstepB, voffB);
;             PG8_WAIT_V(6); PG8_BAR; PG8_MMA(1, 1, At, B1); PG8_BAR;
	v_mfma_f32_16x16x32_bf16 v[60:63], v[136:139], v[156:159], 0
	s_setprio 1
	v_mfma_f32_16x16x32_bf16 v[56:59], v[144:147], v[156:159], 0
	v_mfma_f32_16x16x32_bf16 v[44:47], v[136:139], v[164:167], 0
	v_mfma_f32_16x16x32_bf16 v[40:43], v[144:147], v[164:167], 0
	v_mfma_f32_16x16x32_bf16 v[28:31], v[136:139], v[172:175], 0
	v_mfma_f32_16x16x32_bf16 v[24:27], v[144:147], v[172:175], 0
	v_mfma_f32_16x16x32_bf16 v[12:15], v[136:139], v[180:183], 0
	v_mfma_f32_16x16x32_bf16 v[8:11], v[144:147], v[180:183], 0
	v_mfma_f32_16x16x32_bf16 v[60:63], v[140:143], v[160:163], v[60:63]
	v_mfma_f32_16x16x32_bf16 v[56:59], v[148:151], v[160:163], v[56:59]
	v_mfma_f32_16x16x32_bf16 v[44:47], v[140:143], v[168:171], v[44:47]
	v_mfma_f32_16x16x32_bf16 v[40:43], v[148:151], v[168:171], v[40:43]
	v_mfma_f32_16x16x32_bf16 v[28:31], v[140:143], v[176:179], v[28:31]
	v_mfma_f32_16x16x32_bf16 v[24:27], v[148:151], v[176:179], v[24:27]
	v_mfma_f32_16x16x32_bf16 v[12:15], v[140:143], v[184:187], v[12:15]
	v_mfma_f32_16x16x32_bf16 v[8:11], v[148:151], v[184:187], v[8:11]
	v_mfma_f32_16x16x32_bf16 v[52:55], v[188:191], v[156:159], 0
	v_mfma_f32_16x16x32_bf16 v[48:51], v[196:199], v[156:159], 0
	s_add_i32 s55, 0, 0x18000
	v_add_u32_e32 v148, s55, v134
	v_mfma_f32_16x16x32_bf16 v[36:39], v[188:191], v[164:167], 0
	v_mfma_f32_16x16x32_bf16 v[32:35], v[196:199], v[164:167], 0
	v_mfma_f32_16x16x32_bf16 v[20:23], v[188:191], v[172:175], 0
	v_mfma_f32_16x16x32_bf16 v[16:19], v[196:199], v[172:175], 0
	v_mfma_f32_16x16x32_bf16 v[4:7], v[188:191], v[180:183], 0
	v_mfma_f32_16x16x32_bf16 v[0:3], v[196:199], v[180:183], 0
	v_mfma_f32_16x16x32_bf16 v[52:55], v[192:195], v[160:163], v[52:55]
	v_mfma_f32_16x16x32_bf16 v[48:51], v[200:203], v[160:163], v[48:51]
	v_mfma_f32_16x16x32_bf16 v[36:39], v[192:195], v[168:171], v[36:39]
	v_mfma_f32_16x16x32_bf16 v[32:35], v[200:203], v[168:171], v[32:35]
	v_mfma_f32_16x16x32_bf16 v[20:23], v[192:195], v[176:179], v[20:23]
	v_mfma_f32_16x16x32_bf16 v[16:19], v[200:203], v[176:179], v[16:19]
	v_mfma_f32_16x16x32_bf16 v[4:7], v[192:195], v[184:187], v[4:7]
	s_setprio 0
	v_mfma_f32_16x16x32_bf16 v[0:3], v[200:203], v[184:187], v[0:3]
	s_barrier
	s_add_u32 s28, s28, 0x80000
	s_addc_u32 s29, s29, 0
	s_mov_b32 m0, s39
	v_lshl_add_u64 v[188:189], s[28:29], 0, v[128:129]
	global_load_lds_dwordx4 v[188:189], off
	s_mov_b32 m0, s40
	v_lshl_add_u64 v[188:189], s[28:29], 0, v[130:131]
	global_load_lds_dwordx4 v[188:189], off
	ds_read_b128 v[136:139], v148
	ds_read_b128 v[144:147], v148 offset:2048
	ds_read_b128 v[140:143], v148 offset:1024
	ds_read_b128 v[148:151], v148 offset:3072
	ds_read_b128 v[156:159], v135 offset:32768
	ds_read_b128 v[164:167], v135 offset:34816
	ds_read_b128 v[172:175], v135 offset:36864
	ds_read_b128 v[180:183], v135 offset:38912
	ds_read_b128 v[160:163], v135 offset:33792
	ds_read_b128 v[168:171], v135 offset:35840
	ds_read_b128 v[176:179], v135 offset:37888
	ds_read_b128 v[184:187], v135 offset:39936
	s_mov_b32 s56, 0x1c000
	s_add_u32 s28, s24, 0x4000
	s_addc_u32 s29, s25, 0
	s_add_i32 s55, s55, s36
	v_add_u32_e32 v152, s56, v134
	ds_read_b128 v[188:191], v152
	ds_read_b128 v[196:199], v152 offset:2048
	ds_read_b128 v[192:195], v152 offset:1024
	ds_read_b128 v[200:203], v152 offset:3072
	s_waitcnt vmcnt(8)
	s_waitcnt lgkmcnt(0)
	s_barrier
	v_mfma_f32_16x16x32_bf16 v[124:127], v[136:139], v[156:159], v[124:127]
	s_setprio 1
	v_mfma_f32_16x16x32_bf16 v[120:123], v[144:147], v[156:159], v[120:123]
	v_mfma_f32_16x16x32_bf16 v[108:111], v[136:139], v[164:167], v[108:111]
	v_mfma_f32_16x16x32_bf16 v[104:107], v[144:147], v[164:167], v[104:107]
	v_mfma_f32_16x16x32_bf16 v[92:95], v[136:139], v[172:175], v[92:95]
	v_mfma_f32_16x16x32_bf16 v[88:91], v[144:147], v[172:175], v[88:91]
	v_mfma_f32_16x16x32_bf16 v[76:79], v[136:139], v[180:183], v[76:79]
	v_mfma_f32_16x16x32_bf16 v[72:75], v[144:147], v[180:183], v[72:75]
	v_mfma_f32_16x16x32_bf16 v[124:127], v[140:143], v[160:163], v[124:127]
	v_mfma_f32_16x16x32_bf16 v[120:123], v[148:151], v[160:163], v[120:123]
	v_mfma_f32_16x16x32_bf16 v[108:111], v[140:143], v[168:171], v[108:111]
	v_mfma_f32_16x16x32_bf16 v[104:107], v[148:151], v[168:171], v[104:107]
	v_mfma_f32_16x16x32_bf16 v[92:95], v[140:143], v[176:179], v[92:95]
	v_mfma_f32_16x16x32_bf16 v[88:91], v[148:151], v[176:179], v[88:91]
	v_mfma_f32_16x16x32_bf16 v[76:79], v[140:143], v[184:187], v[76:79]
	v_mfma_f32_16x16x32_bf16 v[72:75], v[148:151], v[184:187], v[72:75]
	v_mfma_f32_16x16x32_bf16 v[116:119], v[188:191], v[156:159], v[116:119]
	v_mfma_f32_16x16x32_bf16 v[112:115], v[196:199], v[156:159], v[112:115]
	v_mfma_f32_16x16x32_bf16 v[100:103], v[188:191], v[164:167], v[100:103]
	v_mfma_f32_16x16x32_bf16 v[96:99], v[196:199], v[164:167], v[96:99]
	v_mfma_f32_16x16x32_bf16 v[84:87], v[188:191], v[172:175], v[84:87]
	v_mfma_f32_16x16x32_bf16 v[80:83], v[196:199], v[172:175], v[80:83]
	v_mfma_f32_16x16x32_bf16 v[68:71], v[188:191], v[180:183], v[68:71]
	v_mfma_f32_16x16x32_bf16 v[64:67], v[196:199], v[180:183], v[64:67]
	v_mfma_f32_16x16x32_bf16 v[116:119], v[192:195], v[160:163], v[116:119]
	v_mfma_f32_16x16x32_bf16 v[112:115], v[200:203], v[160:163], v[112:115]
	v_mfma_f32_16x16x32_bf16 v[100:103], v[192:195], v[168:171], v[100:103]
	v_mfma_f32_16x16x32_bf16 v[96:99], v[200:203], v[168:171], v[96:99]
	v_mfma_f32_16x16x32_bf16 v[84:87], v[192:195], v[176:179], v[84:87]
	v_mfma_f32_16x16x32_bf16 v[80:83], v[200:203], v[176:179], v[80:83]
	v_mfma_f32_16x16x32_bf16 v[68:71], v[192:195], v[184:187], v[68:71]
	s_setprio 0
	v_mfma_f32_16x16x32_bf16 v[64:67], v[200:203], v[184:187], v[64:67]
	s_barrier
; #define PG8_STAGE(bufoff, gbase, voff) do { _Pragma("unroll") for (int _i = 0; _i < 2; ++_i) \
;         __builtin_amdgcn_global_load_lds((const unsigned*)((const char*)(gbase) + (voff)[_i]), (LAS unsigned*)(lds + (bufoff) + ldsw + _i * 8192), 16, 0, 0); } while (0)
; #define PG8_LDA(dst, b, h) do { _Pragma("unroll") for (int m = 0; m < 4; ++m) _Pragma("unroll") for (int k = 0; k < 2; ++k) dst[m][k] = *(const LAS bf16x8*)(lds + PG8_SA(b, h) + aoff + m * 2048 + k * 1024); } while (0)
; #define PG8_WAIT_V(n) asm volatile("s_waitcnt vmcnt(" #n ")" ::: "memory")
; #define PG8_WAIT_L(n) asm volatile("s_waitcnt lgkmcnt(" #n ")" ::: "memory")
; template <class Epi>
; __device__ __forceinline__ void gemm_phase(LAS unsigned char* lds, const Gemm g, const StaticOrder& S, const Epi& E) {
;     ...
;         for (int t = 0; t < nt; t += 2) {
;             const bool last = (t == nt - 2);
;             const char* a1 = cA + (size_t)(t + 1) * kstep;
;             const char* a2 = last ? nA : cA + (size_t)(t + 2) * kstep; const char* b2 = last ? nB : cB + (size_t)(t + 2) * kstep;
;             const char* a3 = a2 + kstep; const char* b3 = b2 + kstep;
;             PG8_LDB(B0, 0, 0); PG8_SCHED; PG8_LDA(At, 0, 0); PG8_STAGE(PG8_SA(1, 1), a1 + hstepA, voffA);
;             PG8_WAIT_L(8); PG8_BAR; PG8_WAIT_L(0); PG8_MMA(0, 0, At, B0); PG8_BAR; PG8_SCHED;
;             PG8_LDB(B1, 0, 1); PG8_STAGE(PG8_SB(0, 0), b2, voffB);
;             PG8_BAR; PG8_WAIT_L(0); PG8_MMA(0, 1, At, B1); PG8_BAR;
;             PG8_LDA(At, 0, 1); PG8_STAGE(PG8_SA(0, 0), a2, voffA);
;             PG8_BAR; PG8_WAIT_L(0); PG8_MMA(1, 0, At, B0); PG8_BAR; PG8_SCHED;
;             PG8_STAGE(PG8_SB(0, 1), b2 + hstepB, voffB);
;             PG8_WAIT_V(6); PG8_BAR; PG8_MMA(1, 1, At, B1); PG8_BAR;
;             PG8_LDB(B0, 1, 0); PG8_SCHED; PG8_LDA(At, 1, 0); PG8_STAGE(PG8_SA(0, 1), a2 + hstepA, voffA);
;             PG8_WAIT_L(8); PG8_BAR; PG8_WAIT_L(0); PG8_MMA(0, 0, At, B0); PG8_BAR; PG8_SCHED;
;             PG8_LDB(B1, 1, 1); PG8_STAGE(PG8_SB(1, 0), b3, voffB);
;             PG8_BAR; PG8_WAIT_L(0); PG8_MMA(0, 1, At, B1); PG8_BAR;
;             PG8_LDA(At, 1, 1); PG8_STAGE(PG8_SA(1, 0), a3, voffA);
;             PG8_BAR; PG8_WAIT_L(0); PG8_MMA(1, 0, At, B0); PG8_BAR; PG8_SCHED;
;             PG8_STAGE(PG8_SB(1, 1), b3 + hstepB, voffB);
;             PG8_WAIT_V(6); PG8_BAR; PG8_MMA(1, 1, At, B1); PG8_BAR;
	s_mov_b32 m0, s55
	v_lshl_add_u64 v[204:205], s[28:29], 0, v[128:129]
	global_load_lds_dwordx4 v[204:205], off
	s_add_i32 m0, s55, 0x2000
	v_lshl_add_u64 v[204:205], s[28:29], 0, v[130:131]
	global_load_lds_dwordx4 v[204:205], off
	s_mov_b32 m0, s43
	v_lshl_add_u64 v[204:205], s[26:27], 0, v[128:129]
	global_load_lds_dwordx4 v[204:205], off
	s_mov_b32 m0, s44
	v_lshl_add_u64 v[204:205], s[26:27], 0, v[130:131]
	global_load_lds_dwordx4 v[204:205], off
	s_add_u32 s24, s24, 0x84000
	s_addc_u32 s25, s25, 0
	s_add_i32 s26, s56, s36
	s_mov_b32 m0, s26
	v_lshl_add_u64 v[204:205], s[24:25], 0, v[128:129]
	global_load_lds_dwordx4 v[204:205], off
	s_add_i32 m0, s26, 0x2000
	v_lshl_add_u64 v[204:205], s[24:25], 0, v[130:131]
	global_load_lds_dwordx4 v[204:205], off
	ds_read_b128 v[156:159], v135 offset:49152
	ds_read_b128 v[164:167], v135 offset:51200
	ds_read_b128 v[172:175], v135 offset:53248
	ds_read_b128 v[180:183], v135 offset:55296
	ds_read_b128 v[160:163], v135 offset:50176
	ds_read_b128 v[168:171], v135 offset:52224
	ds_read_b128 v[176:179], v135 offset:54272
	ds_read_b128 v[184:187], v135 offset:56320
	s_waitcnt vmcnt(8)
	s_waitcnt lgkmcnt(0)
	s_barrier
	v_mfma_f32_16x16x32_bf16 v[60:63], v[136:139], v[156:159], v[60:63]
	s_setprio 1
	v_mfma_f32_16x16x32_bf16 v[56:59], v[144:147], v[156:159], v[56:59]
	v_mfma_f32_16x16x32_bf16 v[44:47], v[136:139], v[164:167], v[44:47]
	v_mfma_f32_16x16x32_bf16 v[40:43], v[144:147], v[164:167], v[40:43]
	v_mfma_f32_16x16x32_bf16 v[28:31], v[136:139], v[172:175], v[28:31]
	v_mfma_f32_16x16x32_bf16 v[24:27], v[144:147], v[172:175], v[24:27]
	v_mfma_f32_16x16x32_bf16 v[12:15], v[136:139], v[180:183], v[12:15]
	v_mfma_f32_16x16x32_bf16 v[8:11], v[144:147], v[180:183], v[8:11]
	v_mfma_f32_16x16x32_bf16 v[60:63], v[140:143], v[160:163], v[60:63]
	v_mfma_f32_16x16x32_bf16 v[56:59], v[148:151], v[160:163], v[56:59]
	v_mfma_f32_16x16x32_bf16 v[44:47], v[140:143], v[168:171], v[44:47]
	v_mfma_f32_16x16x32_bf16 v[40:43], v[148:151], v[168:171], v[40:43]
	v_mfma_f32_16x16x32_bf16 v[28:31], v[140:143], v[176:179], v[28:31]
	v_mfma_f32_16x16x32_bf16 v[24:27], v[148:151], v[176:179], v[24:27]
	v_mfma_f32_16x16x32_bf16 v[12:15], v[140:143], v[184:187], v[12:15]
	v_mfma_f32_16x16x32_bf16 v[8:11], v[148:151], v[184:187], v[8:11]
	v_mfma_f32_16x16x32_bf16 v[52:55], v[188:191], v[156:159], v[52:55]
	v_mfma_f32_16x16x32_bf16 v[48:51], v[196:199], v[156:159], v[48:51]
	s_add_i32 s54, s54, 2
	s_add_u32 s22, s22, 0x8000
	s_addc_u32 s23, s23, 0
	s_add_u32 s51, s51, 0x8000
	s_addc_u32 s52, s52, 0
	v_mfma_f32_16x16x32_bf16 v[36:39], v[188:191], v[164:167], v[36:39]
	v_mfma_f32_16x16x32_bf16 v[32:35], v[196:199], v[164:167], v[32:35]
	v_mfma_f32_16x16x32_bf16 v[20:23], v[188:191], v[172:175], v[20:23]
	v_mfma_f32_16x16x32_bf16 v[16:19], v[196:199], v[172:175], v[16:19]
	v_mfma_f32_16x16x32_bf16 v[4:7], v[188:191], v[180:183], v[4:7]
	v_mfma_f32_16x16x32_bf16 v[0:3], v[196:199], v[180:183], v[0:3]
	v_mfma_f32_16x16x32_bf16 v[52:55], v[192:195], v[160:163], v[52:55]
	v_mfma_f32_16x16x32_bf16 v[48:51], v[200:203], v[160:163], v[48:51]
	v_mfma_f32_16x16x32_bf16 v[36:39], v[192:195], v[168:171], v[36:39]
	v_mfma_f32_16x16x32_bf16 v[32:35], v[200:203], v[168:171], v[32:35]
	v_mfma_f32_16x16x32_bf16 v[20:23], v[192:195], v[176:179], v[20:23]
	v_mfma_f32_16x16x32_bf16 v[16:19], v[200:203], v[176:179], v[16:19]
	v_mfma_f32_16x16x32_bf16 v[4:7], v[192:195], v[184:187], v[4:7]
	s_cmp_gt_u32 s54, 29
	s_setprio 0
	v_mfma_f32_16x16x32_bf16 v[0:3], v[200:203], v[184:187], v[0:3]
	s_barrier
	s_cbranch_scc0 .LBB0_141
	s_branch .Lpeel_done_141
.LBB0_141:
	s_add_u32 s24, s22, 0xfff84000
	s_addc_u32 s25, s23, -1
	s_cmp_eq_u32 s54, 28
	s_cselect_b32 s28, s49, s24
	s_cselect_b32 s29, s15, s25
	s_cselect_b32 s24, s50, s51
	s_cselect_b32 s25, s5, s52
	s_add_u32 s26, s28, 0x4000
	s_addc_u32 s27, s29, 0
	s_add_i32 m0, s37, 0xc000
	v_lshl_add_u64 v[188:189], s[22:23], 0, v[128:129]
	global_load_lds_dwordx4 v[188:189], off
	s_add_i32 m0, s37, 0xe000
	v_lshl_add_u64 v[188:189], s[22:23], 0, v[130:131]
	global_load_lds_dwordx4 v[188:189], off
	s_mov_b32 s55, 0x10000
	v_add_u32_e32 v148, s55, v134
	ds_read_b128 v[136:139], v148
	ds_read_b128 v[144:147], v148 offset:2048
	ds_read_b128 v[140:143], v148 offset:1024
	ds_read_b128 v[148:151], v148 offset:3072
	ds_read_b128 v[156:159], v135
	ds_read_b128 v[164:167], v135 offset:2048
	ds_read_b128 v[172:175], v135 offset:4096
	ds_read_b128 v[180:183], v135 offset:6144
	ds_read_b128 v[160:163], v135 offset:1024
	ds_read_b128 v[168:171], v135 offset:3072
	ds_read_b128 v[176:179], v135 offset:5120
	ds_read_b128 v[184:187], v135 offset:7168
	s_mov_b32 s58, 0x14000
	s_add_i32 s55, s55, s36
	v_add_u32_e32 v152, s58, v134
	ds_read_b128 v[188:191], v152
	ds_read_b128 v[196:199], v152 offset:2048
	ds_read_b128 v[192:195], v152 offset:1024
	ds_read_b128 v[200:203], v152 offset:3072
	s_waitcnt vmcnt(8)
	s_waitcnt lgkmcnt(0)
	s_barrier
; #define PG8_STAGE(bufoff, gbase, voff) do { _Pragma("unroll") for (int _i = 0; _i < 2; ++_i) \
;         __builtin_amdgcn_global_load_lds((const unsigned*)((const char*)(gbase) + (voff)[_i]), (LAS unsigned*)(lds + (bufoff) + ldsw + _i * 8192), 16, 0, 0); } while (0)
; #define PG8_LDA(dst, b, h) do { _Pragma("unroll") for (int m = 0; m < 4; ++m) _Pragma("unroll") for (int k = 0; k < 2; ++k) dst[m][k] = *(const LAS bf16x8*)(lds + PG8_SA(b, h) + aoff + m * 2048 + k * 1024); } while (0)
; #define PG8_LDB(dst, b, h) do { _Pragma("unroll") for (int n = 0; n < 2; ++n) _Pragma("unroll") for (int k = 0; k < 2; ++k) dst[n][k] = *(const LAS bf16x8*)(lds + PG8_SB(b, h) + boff + n * 2048 + k * 1024); } while (0)
; #define PG8_WAIT_V(n) asm volatile("s_waitcnt vmcnt(" #n ")" ::: "memory")
; #define PG8_WAIT_L(n) asm volatile("s_waitcnt lgkmcnt(" #n ")" ::: "memory")
; #define PG8_BAR __builtin_amdgcn_s_barrier()
; #define PG8_SCHED __builtin_amdgcn_sched_barrier(0)
; template <class Epi>
; __device__ __forceinline__ void gemm_phase(LAS unsigned char* lds, const Gemm g, const StaticOrder& S, const Epi& E) {
;     ...
;             PG8_LDB(B0, 0, 0); PG8_SCHED; PG8_LDA(At, 0, 0); PG8_STAGE(PG8_SA(1, 1), a1 + hstepA, voffA);
;             PG8_WAIT_L(8); PG8_BAR; PG8_WAIT_L(0); PG8_MMA(0, 0, At, B0); PG8_BAR; PG8_SCHED;
;             PG8_LDB(B1, 0, 1); PG8_STAGE(PG8_SB(0, 0), b2, voffB);
;             PG8_BAR; PG8_WAIT_L(0); PG8_MMA(0, 1, At, B1); PG8_BAR;
;             PG8_LDA(At, 0, 1); PG8_STAGE(PG8_SA(0, 0), a2, voffA);
;             PG8_BAR; PG8_WAIT_L(0); PG8_MMA(1, 0, At, B0); PG8_BAR; PG8_SCHED;
;             PG8_STAGE(PG8_SB(0, 1), b2 + hstepB, voffB);
;             PG8_WAIT_V(6); PG8_BAR; PG8_MMA(1, 1, At, B1); PG8_BAR;
;             PG8_LDB(B0, 1, 0); PG8_SCHED; PG8_LDA(At, 1, 0); PG8_STAGE(PG8_SA(0, 1), a2 + hstepA, voffA);
;             PG8_WAIT_L(8); PG8_BAR; PG8_WAIT_L(0); PG8_MMA(0, 0, At, B0); PG8_BAR; PG8_SCHED;
;             PG8_LDB(B1, 1, 1); PG8_STAGE(PG8_SB(1, 0), b3, voffB);
;             PG8_BAR; PG8_WAIT_L(0); PG8_MMA(0, 1, At, B1); PG8_BAR;
;             PG8_LDA(At, 1, 1); PG8_STAGE(PG8_SA(1, 0), a3, voffA);
;             PG8_BAR; PG8_WAIT_L(0); PG8_MMA(1, 0, At, B0); PG8_BAR; PG8_SCHED;
;             PG8_STAGE(PG8_SB(1, 1), b3 + hstepB, voffB);
;             PG8_WAIT_V(6); PG8_BAR; PG8_MMA(1, 1, At, B1); PG8_BAR;
	v_mfma_f32_16x16x32_bf16 v[124:127], v[136:139], v[156:159], v[124:127]
	s_setprio 1
	v_mfma_f32_16x16x32_bf16 v[120:123], v[144:147], v[156:159], v[120:123]
	v_mfma_f32_16x16x32_bf16 v[108:111], v[136:139], v[164:167], v[108:111]
	v_mfma_f32_16x16x32_bf16 v[104:107], v[144:147], v[164:167], v[104:107]
	v_mfma_f32_16x16x32_bf16 v[92:95], v[136:139], v[172:175], v[92:95]
	v_mfma_f32_16x16x32_bf16 v[88:91], v[144:147], v[172:175], v[88:91]
	v_mfma_f32_16x16x32_bf16 v[76:79], v[136:139], v[180:183], v[76:79]
	v_mfma_f32_16x16x32_bf16 v[72:75], v[144:147], v[180:183], v[72:75]
	v_mfma_f32_16x16x32_bf16 v[124:127], v[140:143], v[160:163], v[124:127]
	v_mfma_f32_16x16x32_bf16 v[120:123], v[148:151], v[160:163], v[120:123]
	v_mfma_f32_16x16x32_bf16 v[108:111], v[140:143], v[168:171], v[108:111]
	v_mfma_f32_16x16x32_bf16 v[104:107], v[148:151], v[168:171], v[104:107]
	v_mfma_f32_16x16x32_bf16 v[92:95], v[140:143], v[176:179], v[92:95]
	v_mfma_f32_16x16x32_bf16 v[88:91], v[148:151], v[176:179], v[88:91]
	v_mfma_f32_16x16x32_bf16 v[76:79], v[140:143], v[184:187], v[76:79]
	v_mfma_f32_16x16x32_bf16 v[72:75], v[148:151], v[184:187], v[72:75]
	v_mfma_f32_16x16x32_bf16 v[116:119], v[188:191], v[156:159], v[116:119]
	v_mfma_f32_16x16x32_bf16 v[112:115], v[196:199], v[156:159], v[112:115]
	v_mfma_f32_16x16x32_bf16 v[100:103], v[188:191], v[164:167], v[100:103]
	v_mfma_f32_16x16x32_bf16 v[96:99], v[196:199], v[164:167], v[96:99]
	v_mfma_f32_16x16x32_bf16 v[84:87], v[188:191], v[172:175], v[84:87]
	v_mfma_f32_16x16x32_bf16 v[80:83], v[196:199], v[172:175], v[80:83]
	v_mfma_f32_16x16x32_bf16 v[68:71], v[188:191], v[180:183], v[68:71]
	v_mfma_f32_16x16x32_bf16 v[64:67], v[196:199], v[180:183], v[64:67]
	v_mfma_f32_16x16x32_bf16 v[116:119], v[192:195], v[160:163], v[116:119]
	v_mfma_f32_16x16x32_bf16 v[112:115], v[200:203], v[160:163], v[112:115]
	v_mfma_f32_16x16x32_bf16 v[100:103], v[192:195], v[168:171], v[100:103]
	v_mfma_f32_16x16x32_bf16 v[96:99], v[200:203], v[168:171], v[96:99]
	v_mfma_f32_16x16x32_bf16 v[84:87], v[192:195], v[176:179], v[84:87]
	v_mfma_f32_16x16x32_bf16 v[80:83], v[200:203], v[176:179], v[80:83]
	v_mfma_f32_16x16x32_bf16 v[68:71], v[192:195], v[184:187], v[68:71]
	s_setprio 0
	v_mfma_f32_16x16x32_bf16 v[64:67], v[200:203], v[184:187], v[64:67]
	s_barrier
	s_mov_b32 m0, s55
	v_lshl_add_u64 v[204:205], s[24:25], 0, v[128:129]
	global_load_lds_dwordx4 v[204:205], off
	s_add_i32 m0, s55, 0x2000
	v_lshl_add_u64 v[204:205], s[24:25], 0, v[130:131]
	global_load_lds_dwordx4 v[204:205], off
	s_mov_b32 m0, s37
	v_lshl_add_u64 v[204:205], s[28:29], 0, v[128:129]
	global_load_lds_dwordx4 v[204:205], off
	s_mov_b32 m0, s38
	v_lshl_add_u64 v[204:205], s[28:29], 0, v[130:131]
	global_load_lds_dwordx4 v[204:205], off
	s_add_u32 s56, s24, 0x80000
	s_addc_u32 s57, s25, 0
	s_add_i32 s55, s58, s36
	s_mov_b32 m0, s55
	v_lshl_add_u64 v[204:205], s[56:57], 0, v[128:129]
	global_load_lds_dwordx4 v[204:205], off
	s_add_i32 m0, s55, 0x2000
	v_lshl_add_u64 v[204:205], s[56:57], 0, v[130:131]
	global_load_lds_dwordx4 v[204:205], off
	ds_read_b128 v[156:159], v135 offset:16384
	ds_read_b128 v[164:167], v135 offset:18432
	ds_read_b128 v[172:175], v135 offset:20480
	ds_read_b128 v[180:183], v135 offset:22528
	ds_read_b128 v[160:163], v135 offset:17408
	ds_read_b128 v[168:171], v135 offset:19456
	ds_read_b128 v[176:179], v135 offset:21504
	ds_read_b128 v[184:187], v135 offset:23552
	s_waitcnt vmcnt(8)
	s_waitcnt lgkmcnt(0)
	s_barrier
	v_mfma_f32_16x16x32_bf16 v[60:63], v[136:139], v[156:159], v[60:63]
	s_setprio 1
	v_mfma_f32_16x16x32_bf16 v[56:59], v[144:147], v[156:159], v[56:59]
	v_mfma_f32_16x16x32_bf16 v[44:47], v[136:139], v[164:167], v[44:47]
	v_mfma_f32_16x16x32_bf16 v[40:43], v[144:147], v[164:167], v[40:43]
	v_mfma_f32_16x16x32_bf16 v[28:31], v[136:139], v[172:175], v[28:31]
	v_mfma_f32_16x16x32_bf16 v[24:27], v[144:147], v[172:175], v[24:27]
	v_mfma_f32_16x16x32_bf16 v[12:15], v[136:139], v[180:183], v[12:15]
	v_mfma_f32_16x16x32_bf16 v[8:11], v[144:147], v[180:183], v[8:11]
	v_mfma_f32_16x16x32_bf16 v[60:63], v[140:143], v[160:163], v[60:63]
	v_mfma_f32_16x16x32_bf16 v[56:59], v[148:151], v[160:163], v[56:59]
	v_mfma_f32_16x16x32_bf16 v[44:47], v[140:143], v[168:171], v[44:47]
	v_mfma_f32_16x16x32_bf16 v[40:43], v[148:151], v[168:171], v[40:43]
	v_mfma_f32_16x16x32_bf16 v[28:31], v[140:143], v[176:179], v[28:31]
	v_mfma_f32_16x16x32_bf16 v[24:27], v[148:151], v[176:179], v[24:27]
	v_mfma_f32_16x16x32_bf16 v[12:15], v[140:143], v[184:187], v[12:15]
	v_mfma_f32_16x16x32_bf16 v[8:11], v[148:151], v[184:187], v[8:11]
	v_mfma_f32_16x16x32_bf16 v[52:55], v[188:191], v[156:159], v[52:55]
	v_mfma_f32_16x16x32_bf16 v[48:51], v[196:199], v[156:159], v[48:51]
	s_add_i32 s55, 0, 0x18000
	v_add_u32_e32 v148, s55, v134
	v_mfma_f32_16x16x32_bf16 v[36:39], v[188:191], v[164:167], v[36:39]
	v_mfma_f32_16x16x32_bf16 v[32:35], v[196:199], v[164:167], v[32:35]
	v_mfma_f32_16x16x32_bf16 v[20:23], v[188:191], v[172:175], v[20:23]
	v_mfma_f32_16x16x32_bf16 v[16:19], v[196:199], v[172:175], v[16:19]
	v_mfma_f32_16x16x32_bf16 v[4:7], v[188:191], v[180:183], v[4:7]
	v_mfma_f32_16x16x32_bf16 v[0:3], v[196:199], v[180:183], v[0:3]
	v_mfma_f32_16x16x32_bf16 v[52:55], v[192:195], v[160:163], v[52:55]
	v_mfma_f32_16x16x32_bf16 v[48:51], v[200:203], v[160:163], v[48:51]
	v_mfma_f32_16x16x32_bf16 v[36:39], v[192:195], v[168:171], v[36:39]
	v_mfma_f32_16x16x32_bf16 v[32:35], v[200:203], v[168:171], v[32:35]
	v_mfma_f32_16x16x32_bf16 v[20:23], v[192:195], v[176:179], v[20:23]
	v_mfma_f32_16x16x32_bf16 v[16:19], v[200:203], v[176:179], v[16:19]
	v_mfma_f32_16x16x32_bf16 v[4:7], v[192:195], v[184:187], v[4:7]
	s_setprio 0
	v_mfma_f32_16x16x32_bf16 v[0:3], v[200:203], v[184:187], v[0:3]
	s_barrier
; #define PG8_STAGE(bufoff, gbase, voff) do { _Pragma("unroll") for (int _i = 0; _i < 2; ++_i) \
;         __builtin_amdgcn_global_load_lds((const unsigned*)((const char*)(gbase) + (voff)[_i]), (LAS unsigned*)(lds + (bufoff) + ldsw + _i * 8192), 16, 0, 0); } while (0)
; #define PG8_LDA(dst, b, h) do { _Pragma("unroll") for (int m = 0; m < 4; ++m) _Pragma("unroll") for (int k = 0; k < 2; ++k) dst[m][k] = *(const LAS bf16x8*)(lds + PG8_SA(b, h) + aoff + m * 2048 + k * 1024); } while (0)
; #define PG8_LDB(dst, b, h) do { _Pragma("unroll") for (int n = 0; n < 2; ++n) _Pragma("unroll") for (int k = 0; k < 2; ++k) dst[n][k] = *(const LAS bf16x8*)(lds + PG8_SB(b, h) + boff + n * 2048 + k * 1024); } while (0)
; #define PG8_WAIT_V(n) asm volatile("s_waitcnt vmcnt(" #n ")" ::: "memory")
; #define PG8_WAIT_L(n) asm volatile("s_waitcnt lgkmcnt(" #n ")" ::: "memory")
; #define PG8_BAR __builtin_amdgcn_s_barrier()
; #define PG8_SCHED __builtin_amdgcn_sched_barrier(0)
; template <class Epi>
; __device__ __forceinline__ void gemm_phase(LAS unsigned char* lds, const Gemm g, const StaticOrder& S, const Epi& E) {
;     ...
;             PG8_LDB(B0, 0, 0); PG8_SCHED; PG8_LDA(At, 0, 0); PG8_STAGE(PG8_SA(1, 1), a1 + hstepA, voffA);
;             PG8_WAIT_L(8); PG8_BAR; PG8_WAIT_L(0); PG8_MMA(0, 0, At, B0); PG8_BAR; PG8_SCHED;
;             PG8_LDB(B1, 0, 1); PG8_STAGE(PG8_SB(0, 0), b2, voffB);
;             PG8_BAR; PG8_WAIT_L(0); PG8_MMA(0, 1, At, B1); PG8_BAR;
;             PG8_LDA(At, 0, 1); PG8_STAGE(PG8_SA(0, 0), a2, voffA);
;             PG8_BAR; PG8_WAIT_L(0); PG8_MMA(1, 0, At, B0); PG8_BAR; PG8_SCHED;
;             PG8_STAGE(PG8_SB(0, 1), b2 + hstepB, voffB);
;             PG8_WAIT_V(6); PG8_BAR; PG8_MMA(1, 1, At, B1); PG8_BAR;
;             PG8_LDB(B0, 1, 0); PG8_SCHED; PG8_LDA(At, 1, 0); PG8_STAGE(PG8_SA(0, 1), a2 + hstepA, voffA);
;             PG8_WAIT_L(8); PG8_BAR; PG8_WAIT_L(0); PG8_MMA(0, 0, At, B0); PG8_BAR; PG8_SCHED;
;             PG8_LDB(B1, 1, 1); PG8_STAGE(PG8_SB(1, 0), b3, voffB);
;             PG8_BAR; PG8_WAIT_L(0); PG8_MMA(0, 1, At, B1); PG8_BAR;
;             PG8_LDA(At, 1, 1); PG8_STAGE(PG8_SA(1, 0), a3, voffA);
;             PG8_BAR; PG8_WAIT_L(0); PG8_MMA(1, 0, At, B0); PG8_BAR; PG8_SCHED;
;             PG8_STAGE(PG8_SB(1, 1), b3 + hstepB, voffB);
;             PG8_WAIT_V(6); PG8_BAR; PG8_MMA(1, 1, At, B1); PG8_BAR;
	s_add_u32 s28, s28, 0x80000
	s_addc_u32 s29, s29, 0
	s_mov_b32 m0, s39
	v_lshl_add_u64 v[188:189], s[28:29], 0, v[128:129]
	global_load_lds_dwordx4 v[188:189], off
	s_mov_b32 m0, s40
	v_lshl_add_u64 v[188:189], s[28:29], 0, v[130:131]
	global_load_lds_dwordx4 v[188:189], off
	ds_read_b128 v[136:139], v148
	ds_read_b128 v[144:147], v148 offset:2048
	ds_read_b128 v[140:143], v148 offset:1024
	ds_read_b128 v[148:151], v148 offset:3072
	ds_read_b128 v[156:159], v135 offset:32768
	ds_read_b128 v[164:167], v135 offset:34816
	ds_read_b128 v[172:175], v135 offset:36864
	ds_read_b128 v[180:183], v135 offset:38912
	ds_read_b128 v[160:163], v135 offset:33792
	ds_read_b128 v[168:171], v135 offset:35840
	ds_read_b128 v[176:179], v135 offset:37888
	ds_read_b128 v[184:187], v135 offset:39936
	s_mov_b32 s56, 0x1c000
	s_add_u32 s28, s24, 0x4000
	s_addc_u32 s29, s25, 0
	s_add_i32 s55, s55, s36
	v_add_u32_e32 v152, s56, v134
	ds_read_b128 v[188:191], v152
	ds_read_b128 v[196:199], v152 offset:2048
	ds_read_b128 v[192:195], v152 offset:1024
	ds_read_b128 v[200:203], v152 offset:3072
	s_waitcnt vmcnt(8)
	s_waitcnt lgkmcnt(0)
	s_barrier
	v_mfma_f32_16x16x32_bf16 v[124:127], v[136:139], v[156:159], v[124:127]
	s_setprio 1
	v_mfma_f32_16x16x32_bf16 v[120:123], v[144:147], v[156:159], v[120:123]
	v_mfma_f32_16x16x32_bf16 v[108:111], v[136:139], v[164:167], v[108:111]
	v_mfma_f32_16x16x32_bf16 v[104:107], v[144:147], v[164:167], v[104:107]
	v_mfma_f32_16x16x32_bf16 v[92:95], v[136:139], v[172:175], v[92:95]
	v_mfma_f32_16x16x32_bf16 v[88:91], v[144:147], v[172:175], v[88:91]
	v_mfma_f32_16x16x32_bf16 v[76:79], v[136:139], v[180:183], v[76:79]
	v_mfma_f32_16x16x32_bf16 v[72:75], v[144:147], v[180:183], v[72:75]
	v_mfma_f32_16x16x32_bf16 v[124:127], v[140:143], v[160:163], v[124:127]
	v_mfma_f32_16x16x32_bf16 v[120:123], v[148:151], v[160:163], v[120:123]
	v_mfma_f32_16x16x32_bf16 v[108:111], v[140:143], v[168:171], v[108:111]
	v_mfma_f32_16x16x32_bf16 v[104:107], v[148:151], v[168:171], v[104:107]
	v_mfma_f32_16x16x32_bf16 v[92:95], v[140:143], v[176:179], v[92:95]
	v_mfma_f32_16x16x32_bf16 v[88:91], v[148:151], v[176:179], v[88:91]
	v_mfma_f32_16x16x32_bf16 v[76:79], v[140:143], v[184:187], v[76:79]
	v_mfma_f32_16x16x32_bf16 v[72:75], v[148:151], v[184:187], v[72:75]
	v_mfma_f32_16x16x32_bf16 v[116:119], v[188:191], v[156:159], v[116:119]
	v_mfma_f32_16x16x32_bf16 v[112:115], v[196:199], v[156:159], v[112:115]
	v_mfma_f32_16x16x32_bf16 v[100:103], v[188:191], v[164:167], v[100:103]
	v_mfma_f32_16x16x32_bf16 v[96:99], v[196:199], v[164:167], v[96:99]
	v_mfma_f32_16x16x32_bf16 v[84:87], v[188:191], v[172:175], v[84:87]
	v_mfma_f32_16x16x32_bf16 v[80:83], v[196:199], v[172:175], v[80:83]
	v_mfma_f32_16x16x32_bf16 v[68:71], v[188:191], v[180:183], v[68:71]
	v_mfma_f32_16x16x32_bf16 v[64:67], v[196:199], v[180:183], v[64:67]
	v_mfma_f32_16x16x32_bf16 v[116:119], v[192:195], v[160:163], v[116:119]
	v_mfma_f32_16x16x32_bf16 v[112:115], v[200:203], v[160:163], v[112:115]
	v_mfma_f32_16x16x32_bf16 v[100:103], v[192:195], v[168:171], v[100:103]
	v_mfma_f32_16x16x32_bf16 v[96:99], v[200:203], v[168:171], v[96:99]
	v_mfma_f32_16x16x32_bf16 v[84:87], v[192:195], v[176:179], v[84:87]
	v_mfma_f32_16x16x32_bf16 v[80:83], v[200:203], v[176:179], v[80:83]
	v_mfma_f32_16x16x32_bf16 v[68:71], v[192:195], v[184:187], v[68:71]
	s_setprio 0
	v_mfma_f32_16x16x32_bf16 v[64:67], v[200:203], v[184:187], v[64:67]
	s_barrier
	s_mov_b32 m0, s55
	v_lshl_add_u64 v[204:205], s[28:29], 0, v[128:129]
	global_load_lds_dwordx4 v[204:205], off
	s_add_i32 m0, s55, 0x2000
	v_lshl_add_u64 v[204:205], s[28:29], 0, v[130:131]
	global_load_lds_dwordx4 v[204:205], off
	s_mov_b32 m0, s43
	v_lshl_add_u64 v[204:205], s[26:27], 0, v[128:129]
	global_load_lds_dwordx4 v[204:205], off
	s_mov_b32 m0, s44
	v_lshl_add_u64 v[204:205], s[26:27], 0, v[130:131]
	global_load_lds_dwordx4 v[204:205], off
	s_add_u32 s24, s24, 0x84000
	s_addc_u32 s25, s25, 0
	s_add_i32 s26, s56, s36
	s_mov_b32 m0, s26
	v_lshl_add_u64 v[204:205], s[24:25], 0, v[128:129]
	global_load_lds_dwordx4 v[204:205], off
	s_add_i32 m0, s26, 0x2000
	v_lshl_add_u64 v[204:205], s[24:25], 0, v[130:131]
	global_load_lds_dwordx4 v[204:205], off
	ds_read_b128 v[156:159], v135 offset:49152
	ds_read_b128 v[164:167], v135 offset:51200
	ds_read_b128 v[172:175], v135 offset:53248
	ds_read_b128 v[180:183], v135 offset:55296
	ds_read_b128 v[160:163], v135 offset:50176
	ds_read_b128 v[168:171], v135 offset:52224
	ds_read_b128 v[176:179], v135 offset:54272
	ds_read_b128 v[184:187], v135 offset:56320
	s_waitcnt vmcnt(8)
	s_waitcnt lgkmcnt(0)
	s_barrier
	v_mfma_f32_16x16x32_bf16 v[60:63], v[136:139], v[156:159], v[60:63]
	s_setprio 1
	v_mfma_f32_16x16x32_bf16 v[56:59], v[144:147], v[156:159], v[56:59]
	v_mfma_f32_16x16x32_bf16 v[44:47], v[136:139], v[164:167], v[44:47]
	v_mfma_f32_16x16x32_bf16 v[40:43], v[144:147], v[164:167], v[40:43]
	v_mfma_f32_16x16x32_bf16 v[28:31], v[136:139], v[172:175], v[28:31]
	v_mfma_f32_16x16x32_bf16 v[24:27], v[144:147], v[172:175], v[24:27]
	v_mfma_f32_16x16x32_bf16 v[12:15], v[136:139], v[180:183], v[12:15]
	v_mfma_f32_16x16x32_bf16 v[8:11], v[144:147], v[180:183], v[8:11]
	v_mfma_f32_16x16x32_bf16 v[60:63], v[140:143], v[160:163], v[60:63]
	v_mfma_f32_16x16x32_bf16 v[56:59], v[148:151], v[160:163], v[56:59]
	v_mfma_f32_16x16x32_bf16 v[44:47], v[140:143], v[168:171], v[44:47]
	v_mfma_f32_16x16x32_bf16 v[40:43], v[148:151], v[168:171], v[40:43]
	v_mfma_f32_16x16x32_bf16 v[28:31], v[140:143], v[176:179], v[28:31]
	v_mfma_f32_16x16x32_bf16 v[24:27], v[148:151], v[176:179], v[24:27]
	v_mfma_f32_16x16x32_bf16 v[12:15], v[140:143], v[184:187], v[12:15]
	v_mfma_f32_16x16x32_bf16 v[8:11], v[148:151], v[184:187], v[8:11]
	v_mfma_f32_16x16x32_bf16 v[52:55], v[188:191], v[156:159], v[52:55]
	v_mfma_f32_16x16x32_bf16 v[48:51], v[196:199], v[156:159], v[48:51]
	s_add_i32 s54, s54, 2
	s_add_u32 s22, s22, 0x8000
	s_addc_u32 s23, s23, 0
	s_add_u32 s51, s51, 0x8000
	s_addc_u32 s52, s52, 0
	v_mfma_f32_16x16x32_bf16 v[36:39], v[188:191], v[164:167], v[36:39]
	v_mfma_f32_16x16x32_bf16 v[32:35], v[196:199], v[164:167], v[32:35]
	v_mfma_f32_16x16x32_bf16 v[20:23], v[188:191], v[172:175], v[20:23]
	v_mfma_f32_16x16x32_bf16 v[16:19], v[196:199], v[172:175], v[16:19]
	v_mfma_f32_16x16x32_bf16 v[4:7], v[188:191], v[180:183], v[4:7]
	v_mfma_f32_16x16x32_bf16 v[0:3], v[196:199], v[180:183], v[0:3]
	v_mfma_f32_16x16x32_bf16 v[52:55], v[192:195], v[160:163], v[52:55]
	v_mfma_f32_16x16x32_bf16 v[48:51], v[200:203], v[160:163], v[48:51]
	v_mfma_f32_16x16x32_bf16 v[36:39], v[192:195], v[168:171], v[36:39]
	v_mfma_f32_16x16x32_bf16 v[32:35], v[200:203], v[168:171], v[32:35]
	v_mfma_f32_16x16x32_bf16 v[20:23], v[192:195], v[176:179], v[20:23]
	v_mfma_f32_16x16x32_bf16 v[16:19], v[200:203], v[176:179], v[16:19]
	v_mfma_f32_16x16x32_bf16 v[4:7], v[192:195], v[184:187], v[4:7]
	s_cmp_gt_u32 s54, 29
	s_setprio 0
	v_mfma_f32_16x16x32_bf16 v[0:3], v[200:203], v[184:187], v[0:3]
	s_barrier
	s_cbranch_scc0 .LBB0_141

; #define PG8_STAGE(bufoff, gbase, voff) do { _Pragma("unroll") for (int _i = 0; _i < 2; ++_i) \
;         __builtin_amdgcn_global_load_lds((const unsigned*)((const char*)(gbase) + (voff)[_i]), (LAS unsigned*)(lds + (bufoff) + ldsw + _i * 8192), 16, 0, 0); } while (0)
; #define PG8_LDA(dst, b, h) do { _Pragma("unroll") for (int m = 0; m < 4; ++m) _Pragma("unroll") for (int k = 0; k < 2; ++k) dst[m][k] = *(const LAS bf16x8*)(lds + PG8_SA(b, h) + aoff + m * 2048 + k * 1024); } while (0)
; #define PG8_LDB(dst, b, h) do { _Pragma("unroll") for (int n = 0; n < 2; ++n) _Pragma("unroll") for (int k = 0; k < 2; ++k) dst[n][k] = *(const LAS bf16x8*)(lds + PG8_SB(b, h) + boff + n * 2048 + k * 1024); } while (0)
; #define PG8_MMA(ai, bj, At, Bt) do { __builtin_amdgcn_s_setprio(1); _Pragma("unroll") for (int m = 0; m < 4; ++m) _Pragma("unroll") for (int n = 0; n < 2; ++n) _Pragma("unroll") for (int k = 0; k < 2; ++k) \
;         acc[ai][bj][m][n] = __builtin_amdgcn_mfma_f32_16x16x32_bf16(Bt[n][k], At[m][k], acc[ai][bj][m][n], 0, 0, 0); __builtin_amdgcn_s_setprio(0); } while (0)
; template <class Epi>
; __device__ __forceinline__ void gemm_phase(LAS unsigned char* lds, const Gemm g, const StaticOrder& S, const Epi& E) {
;     ...
;         const char* nA = has_next ? (const char*)g.A + (size_t)nxt.pm * tstepA : cA; const char* nB = has_next ? (const char*)g.Bt + (size_t)nxt.pn * tstepB : cB;
;         for (int t = 0; t < nt; t += 2) {
;             const bool last = (t == nt - 2);
;             const char* a1 = cA + (size_t)(t + 1) * kstep;
;             const char* a2 = last ? nA : cA + (size_t)(t + 2) * kstep; const char* b2 = last ? nB : cB + (size_t)(t + 2) * kstep;
;             const char* a3 = a2 + kstep; const char* b3 = b2 + kstep;
;             PG8_LDB(B0, 0, 0); PG8_SCHED; PG8_LDA(At, 0, 0); PG8_STAGE(PG8_SA(1, 1), a1 + hstepA, voffA);
;             PG8_WAIT_L(8); PG8_BAR; PG8_WAIT_L(0); PG8_MMA(0, 0, At, B0); PG8_BAR; PG8_SCHED;
;             PG8_LDB(B1, 0, 1); PG8_STAGE(PG8_SB(0, 0), b2, voffB);
;             PG8_BAR; PG8_WAIT_L(0); PG8_MMA(0, 1, At, B1); PG8_BAR;
;             PG8_LDA(At, 0, 1); PG8_STAGE(PG8_SA(0, 0), a2, voffA);
;             PG8_BAR; PG8_WAIT_L(0); PG8_MMA(1, 0, At, B0); PG8_BAR; PG8_SCHED;
;             PG8_STAGE(PG8_SB(0, 1), b2 + hstepB, voffB);
;             PG8_WAIT_V(6); PG8_BAR; PG8_MMA(1, 1, At, B1); PG8_BAR;
.LBB0_186:
	s_add_u32 s4, s24, 0x4000
	s_addc_u32 s5, s25, 0
	s_add_u32 s50, s22, 0x8000
	s_addc_u32 s51, s23, 0
	s_mov_b32 s22, 0
	s_add_i32 s54, s22, 2
	s_add_u32 s23, s4, 0x4000
	s_addc_u32 s24, s5, 0
	s_cmp_eq_u32 s40, s22
	s_cselect_b32 s26, s6, s23
	s_cselect_b32 s27, s7, s24
	s_cselect_b32 s24, s20, s50
	s_cselect_b32 s25, s21, s51
	s_add_u32 s22, s26, 0x4000
	s_addc_u32 s23, s27, 0
	s_add_i32 m0, s33, 0xc000
	v_lshl_add_u64 v[186:187], s[4:5], 0, v[158:159]
	global_load_lds_dwordx4 v[186:187], off nt
	s_add_i32 m0, s33, 0xe000
	v_lshl_add_u64 v[186:187], s[4:5], 0, v[160:161]
	global_load_lds_dwordx4 v[186:187], off nt
	s_mov_b32 s55, 0x10000
	v_add_u32_e32 v140, s55, v207
	ds_read_b128 v[128:131], v140
	ds_read_b128 v[136:139], v140 offset:2048
	ds_read_b128 v[132:135], v140 offset:1024
	ds_read_b128 v[140:143], v140 offset:3072
	ds_read_b128 v[144:147], v209
	ds_read_b128 v[162:165], v209 offset:2048
	ds_read_b128 v[170:173], v209 offset:4096
	ds_read_b128 v[178:181], v209 offset:6144
	ds_read_b128 v[148:151], v209 offset:1024
	ds_read_b128 v[166:169], v209 offset:3072
	ds_read_b128 v[174:177], v209 offset:5120
	ds_read_b128 v[182:185], v209 offset:7168
	s_mov_b32 s58, 0x14000
	s_add_i32 s55, s55, s31
	v_add_u32_e32 v198, s58, v207
	ds_read_b128 v[186:189], v198
	ds_read_b128 v[194:197], v198 offset:2048
	ds_read_b128 v[190:193], v198 offset:1024
	ds_read_b128 v[198:201], v198 offset:3072
	s_waitcnt vmcnt(8)
	s_waitcnt lgkmcnt(0)
	s_barrier
	v_mfma_f32_16x16x32_bf16 v[124:127], v[128:131], v[144:147], 0
	s_setprio 1
	v_mfma_f32_16x16x32_bf16 v[120:123], v[136:139], v[144:147], 0
	v_mfma_f32_16x16x32_bf16 v[116:119], v[128:131], v[162:165], 0
	v_mfma_f32_16x16x32_bf16 v[112:115], v[136:139], v[162:165], 0
	v_mfma_f32_16x16x32_bf16 v[108:111], v[128:131], v[170:173], 0
	v_mfma_f32_16x16x32_bf16 v[104:107], v[136:139], v[170:173], 0
	v_mfma_f32_16x16x32_bf16 v[100:103], v[128:131], v[178:181], 0
	v_mfma_f32_16x16x32_bf16 v[96:99], v[136:139], v[178:181], 0
	v_mfma_f32_16x16x32_bf16 v[124:127], v[132:135], v[148:151], v[124:127]
	v_mfma_f32_16x16x32_bf16 v[120:123], v[140:143], v[148:151], v[120:123]
	v_mfma_f32_16x16x32_bf16 v[116:119], v[132:135], v[166:169], v[116:119]
	v_mfma_f32_16x16x32_bf16 v[112:115], v[140:143], v[166:169], v[112:115]
	v_mfma_f32_16x16x32_bf16 v[108:111], v[132:135], v[174:177], v[108:111]
	v_mfma_f32_16x16x32_bf16 v[104:107], v[140:143], v[174:177], v[104:107]
	v_mfma_f32_16x16x32_bf16 v[100:103], v[132:135], v[182:185], v[100:103]
	v_mfma_f32_16x16x32_bf16 v[96:99], v[140:143], v[182:185], v[96:99]
	v_mfma_f32_16x16x32_bf16 v[92:95], v[186:189], v[144:147], 0
	v_mfma_f32_16x16x32_bf16 v[88:91], v[194:197], v[144:147], 0
	v_mfma_f32_16x16x32_bf16 v[84:87], v[186:189], v[162:165], 0
	v_mfma_f32_16x16x32_bf16 v[80:83], v[194:197], v[162:165], 0
	v_mfma_f32_16x16x32_bf16 v[76:79], v[186:189], v[170:173], 0
	v_mfma_f32_16x16x32_bf16 v[72:75], v[194:197], v[170:173], 0
	v_mfma_f32_16x16x32_bf16 v[68:71], v[186:189], v[178:181], 0
	v_mfma_f32_16x16x32_bf16 v[64:67], v[194:197], v[178:181], 0
	v_mfma_f32_16x16x32_bf16 v[92:95], v[190:193], v[148:151], v[92:95]
	v_mfma_f32_16x16x32_bf16 v[88:91], v[198:201], v[148:151], v[88:91]
	v_mfma_f32_16x16x32_bf16 v[84:87], v[190:193], v[166:169], v[84:87]
	v_mfma_f32_16x16x32_bf16 v[80:83], v[198:201], v[166:169], v[80:83]
	v_mfma_f32_16x16x32_bf16 v[76:79], v[190:193], v[174:177], v[76:79]
	v_mfma_f32_16x16x32_bf16 v[72:75], v[198:201], v[174:177], v[72:75]
	v_mfma_f32_16x16x32_bf16 v[68:71], v[190:193], v[182:185], v[68:71]
	s_setprio 0
	v_mfma_f32_16x16x32_bf16 v[64:67], v[198:201], v[182:185], v[64:67]
	s_barrier
	s_mov_b32 m0, s55
	v_lshl_add_u64 v[202:203], s[24:25], 0, v[152:153]
	global_load_lds_dwordx4 v[202:203], off
	s_add_i32 m0, s55, 0x2000
	v_lshl_add_u64 v[202:203], s[24:25], 0, v[156:157]
	global_load_lds_dwordx4 v[202:203], off
	s_mov_b32 m0, s33
	v_lshl_add_u64 v[202:203], s[26:27], 0, v[152:153]
	global_load_lds_dwordx4 v[202:203], off nt
	s_mov_b32 m0, s34
	v_lshl_add_u64 v[202:203], s[26:27], 0, v[156:157]
	global_load_lds_dwordx4 v[202:203], off nt
	s_add_u32 s56, s24, s52
	s_addc_u32 s57, s25, 0
	s_add_i32 s55, s58, s31
	s_mov_b32 m0, s55
	v_lshl_add_u64 v[202:203], s[56:57], 0, v[152:153]
	global_load_lds_dwordx4 v[202:203], off
	s_add_i32 m0, s55, 0x2000
	v_lshl_add_u64 v[202:203], s[56:57], 0, v[156:157]
	global_load_lds_dwordx4 v[202:203], off
	ds_read_b128 v[144:147], v209 offset:16384
	ds_read_b128 v[162:165], v209 offset:18432
	ds_read_b128 v[170:173], v209 offset:20480
	ds_read_b128 v[178:181], v209 offset:22528
	ds_read_b128 v[148:151], v209 offset:17408
	ds_read_b128 v[166:169], v209 offset:19456
	ds_read_b128 v[174:177], v209 offset:21504
	ds_read_b128 v[182:185], v209 offset:23552
	s_waitcnt vmcnt(8)
	s_waitcnt lgkmcnt(0)
	s_barrier
; #define PG8_STAGE(bufoff, gbase, voff) do { _Pragma("unroll") for (int _i = 0; _i < 2; ++_i) \
;         __builtin_amdgcn_global_load_lds((const unsigned*)((const char*)(gbase) + (voff)[_i]), (LAS unsigned*)(lds + (bufoff) + ldsw + _i * 8192), 16, 0, 0); } while (0)
; #define PG8_LDA(dst, b, h) do { _Pragma("unroll") for (int m = 0; m < 4; ++m) _Pragma("unroll") for (int k = 0; k < 2; ++k) dst[m][k] = *(const LAS bf16x8*)(lds + PG8_SA(b, h) + aoff + m * 2048 + k * 1024); } while (0)
; #define PG8_LDB(dst, b, h) do { _Pragma("unroll") for (int n = 0; n < 2; ++n) _Pragma("unroll") for (int k = 0; k < 2; ++k) dst[n][k] = *(const LAS bf16x8*)(lds + PG8_SB(b, h) + boff + n * 2048 + k * 1024); } while (0)
; #define PG8_WAIT_V(n) asm volatile("s_waitcnt vmcnt(" #n ")" ::: "memory")
; #define PG8_WAIT_L(n) asm volatile("s_waitcnt lgkmcnt(" #n ")" ::: "memory")
; #define PG8_BAR __builtin_amdgcn_s_barrier()
; #define PG8_SCHED __builtin_amdgcn_sched_barrier(0)
; template <class Epi>
; __device__ __forceinline__ void gemm_phase(LAS unsigned char* lds, const Gemm g, const StaticOrder& S, const Epi& E) {
;     ...
;             PG8_LDB(B0, 0, 0); PG8_SCHED; PG8_LDA(At, 0, 0); PG8_STAGE(PG8_SA(1, 1), a1 + hstepA, voffA);
;             PG8_WAIT_L(8); PG8_BAR; PG8_WAIT_L(0); PG8_MMA(0, 0, At, B0); PG8_BAR; PG8_SCHED;
;             PG8_LDB(B1, 0, 1); PG8_STAGE(PG8_SB(0, 0), b2, voffB);
;             PG8_BAR; PG8_WAIT_L(0); PG8_MMA(0, 1, At, B1); PG8_BAR;
;             PG8_LDA(At, 0, 1); PG8_STAGE(PG8_SA(0, 0), a2, voffA);
;             PG8_BAR; PG8_WAIT_L(0); PG8_MMA(1, 0, At, B0); PG8_BAR; PG8_SCHED;
;             PG8_STAGE(PG8_SB(0, 1), b2 + hstepB, voffB);
;             PG8_WAIT_V(6); PG8_BAR; PG8_MMA(1, 1, At, B1); PG8_BAR;
;             PG8_LDB(B0, 1, 0); PG8_SCHED; PG8_LDA(At, 1, 0); PG8_STAGE(PG8_SA(0, 1), a2 + hstepA, voffA);
;             PG8_WAIT_L(8); PG8_BAR; PG8_WAIT_L(0); PG8_MMA(0, 0, At, B0); PG8_BAR; PG8_SCHED;
;             PG8_LDB(B1, 1, 1); PG8_STAGE(PG8_SB(1, 0), b3, voffB);
;             PG8_BAR; PG8_WAIT_L(0); PG8_MMA(0, 1, At, B1); PG8_BAR;
;             PG8_LDA(At, 1, 1); PG8_STAGE(PG8_SA(1, 0), a3, voffA);
;             PG8_BAR; PG8_WAIT_L(0); PG8_MMA(1, 0, At, B0); PG8_BAR; PG8_SCHED;
;             PG8_STAGE(PG8_SB(1, 1), b3 + hstepB, voffB);
;             PG8_WAIT_V(6); PG8_BAR; PG8_MMA(1, 1, At, B1); PG8_BAR;
	v_mfma_f32_16x16x32_bf16 v[60:63], v[128:131], v[144:147], 0
	s_setprio 1
	v_mfma_f32_16x16x32_bf16 v[56:59], v[136:139], v[144:147], 0
	v_mfma_f32_16x16x32_bf16 v[52:55], v[128:131], v[162:165], 0
	v_mfma_f32_16x16x32_bf16 v[48:51], v[136:139], v[162:165], 0
	v_mfma_f32_16x16x32_bf16 v[44:47], v[128:131], v[170:173], 0
	v_mfma_f32_16x16x32_bf16 v[40:43], v[136:139], v[170:173], 0
	v_mfma_f32_16x16x32_bf16 v[36:39], v[128:131], v[178:181], 0
	v_mfma_f32_16x16x32_bf16 v[32:35], v[136:139], v[178:181], 0
	v_mfma_f32_16x16x32_bf16 v[60:63], v[132:135], v[148:151], v[60:63]
	v_mfma_f32_16x16x32_bf16 v[56:59], v[140:143], v[148:151], v[56:59]
	v_mfma_f32_16x16x32_bf16 v[52:55], v[132:135], v[166:169], v[52:55]
	v_mfma_f32_16x16x32_bf16 v[48:51], v[140:143], v[166:169], v[48:51]
	v_mfma_f32_16x16x32_bf16 v[44:47], v[132:135], v[174:177], v[44:47]
	v_mfma_f32_16x16x32_bf16 v[40:43], v[140:143], v[174:177], v[40:43]
	v_mfma_f32_16x16x32_bf16 v[36:39], v[132:135], v[182:185], v[36:39]
	v_mfma_f32_16x16x32_bf16 v[32:35], v[140:143], v[182:185], v[32:35]
	v_mfma_f32_16x16x32_bf16 v[28:31], v[186:189], v[144:147], 0
	v_mfma_f32_16x16x32_bf16 v[24:27], v[194:197], v[144:147], 0
	s_add_i32 s55, 0, 0x18000
	v_add_u32_e32 v140, s55, v207
	v_mfma_f32_16x16x32_bf16 v[20:23], v[186:189], v[162:165], 0
	v_mfma_f32_16x16x32_bf16 v[16:19], v[194:197], v[162:165], 0
	v_mfma_f32_16x16x32_bf16 v[12:15], v[186:189], v[170:173], 0
	v_mfma_f32_16x16x32_bf16 v[8:11], v[194:197], v[170:173], 0
	v_mfma_f32_16x16x32_bf16 v[4:7], v[186:189], v[178:181], 0
	v_mfma_f32_16x16x32_bf16 v[0:3], v[194:197], v[178:181], 0
	v_mfma_f32_16x16x32_bf16 v[28:31], v[190:193], v[148:151], v[28:31]
	v_mfma_f32_16x16x32_bf16 v[24:27], v[198:201], v[148:151], v[24:27]
	v_mfma_f32_16x16x32_bf16 v[20:23], v[190:193], v[166:169], v[20:23]
	v_mfma_f32_16x16x32_bf16 v[16:19], v[198:201], v[166:169], v[16:19]
	v_mfma_f32_16x16x32_bf16 v[12:15], v[190:193], v[174:177], v[12:15]
	v_mfma_f32_16x16x32_bf16 v[8:11], v[198:201], v[174:177], v[8:11]
	v_mfma_f32_16x16x32_bf16 v[4:7], v[190:193], v[182:185], v[4:7]
	s_setprio 0
	v_mfma_f32_16x16x32_bf16 v[0:3], v[198:201], v[182:185], v[0:3]
	s_barrier
	s_add_u32 s26, s26, s52
	s_addc_u32 s27, s27, 0
	s_mov_b32 m0, s35
	v_lshl_add_u64 v[186:187], s[26:27], 0, v[152:153]
	global_load_lds_dwordx4 v[186:187], off nt
	s_mov_b32 m0, s36
	v_lshl_add_u64 v[186:187], s[26:27], 0, v[156:157]
	global_load_lds_dwordx4 v[186:187], off nt
	ds_read_b128 v[128:131], v140
	ds_read_b128 v[136:139], v140 offset:2048
	ds_read_b128 v[132:135], v140 offset:1024
	ds_read_b128 v[140:143], v140 offset:3072
	ds_read_b128 v[144:147], v209 offset:32768
	ds_read_b128 v[162:165], v209 offset:34816
	ds_read_b128 v[170:173], v209 offset:36864
	ds_read_b128 v[178:181], v209 offset:38912
	ds_read_b128 v[148:151], v209 offset:33792
	ds_read_b128 v[166:169], v209 offset:35840
	ds_read_b128 v[174:177], v209 offset:37888
	ds_read_b128 v[182:185], v209 offset:39936
	s_mov_b32 s26, 0x1c000
	s_add_u32 s24, s24, 0x4000
	s_addc_u32 s25, s25, 0
	s_add_i32 s27, s55, s31
	v_add_u32_e32 v198, s26, v207
	ds_read_b128 v[186:189], v198
	ds_read_b128 v[194:197], v198 offset:2048
	ds_read_b128 v[190:193], v198 offset:1024
	ds_read_b128 v[198:201], v198 offset:3072
	s_waitcnt vmcnt(8)
	s_waitcnt lgkmcnt(0)
	s_barrier
	v_mfma_f32_16x16x32_bf16 v[124:127], v[128:131], v[144:147], v[124:127]
	s_setprio 1
	v_mfma_f32_16x16x32_bf16 v[120:123], v[136:139], v[144:147], v[120:123]
	v_mfma_f32_16x16x32_bf16 v[116:119], v[128:131], v[162:165], v[116:119]
	v_mfma_f32_16x16x32_bf16 v[112:115], v[136:139], v[162:165], v[112:115]
	v_mfma_f32_16x16x32_bf16 v[108:111], v[128:131], v[170:173], v[108:111]
	v_mfma_f32_16x16x32_bf16 v[104:107], v[136:139], v[170:173], v[104:107]
	v_mfma_f32_16x16x32_bf16 v[100:103], v[128:131], v[178:181], v[100:103]
	v_mfma_f32_16x16x32_bf16 v[96:99], v[136:139], v[178:181], v[96:99]
	v_mfma_f32_16x16x32_bf16 v[124:127], v[132:135], v[148:151], v[124:127]
	v_mfma_f32_16x16x32_bf16 v[120:123], v[140:143], v[148:151], v[120:123]
	v_mfma_f32_16x16x32_bf16 v[116:119], v[132:135], v[166:169], v[116:119]
	v_mfma_f32_16x16x32_bf16 v[112:115], v[140:143], v[166:169], v[112:115]
	v_mfma_f32_16x16x32_bf16 v[108:111], v[132:135], v[174:177], v[108:111]
	v_mfma_f32_16x16x32_bf16 v[104:107], v[140:143], v[174:177], v[104:107]
	v_mfma_f32_16x16x32_bf16 v[100:103], v[132:135], v[182:185], v[100:103]
	v_mfma_f32_16x16x32_bf16 v[96:99], v[140:143], v[182:185], v[96:99]
	v_mfma_f32_16x16x32_bf16 v[92:95], v[186:189], v[144:147], v[92:95]
	v_mfma_f32_16x16x32_bf16 v[88:91], v[194:197], v[144:147], v[88:91]
	v_mfma_f32_16x16x32_bf16 v[84:87], v[186:189], v[162:165], v[84:87]
	v_mfma_f32_16x16x32_bf16 v[80:83], v[194:197], v[162:165], v[80:83]
	v_mfma_f32_16x16x32_bf16 v[76:79], v[186:189], v[170:173], v[76:79]
	v_mfma_f32_16x16x32_bf16 v[72:75], v[194:197], v[170:173], v[72:75]
	v_mfma_f32_16x16x32_bf16 v[68:71], v[186:189], v[178:181], v[68:71]
	v_mfma_f32_16x16x32_bf16 v[64:67], v[194:197], v[178:181], v[64:67]
	v_mfma_f32_16x16x32_bf16 v[92:95], v[190:193], v[148:151], v[92:95]
	v_mfma_f32_16x16x32_bf16 v[88:91], v[198:201], v[148:151], v[88:91]
	v_mfma_f32_16x16x32_bf16 v[84:87], v[190:193], v[166:169], v[84:87]
	v_mfma_f32_16x16x32_bf16 v[80:83], v[198:201], v[166:169], v[80:83]
	v_mfma_f32_16x16x32_bf16 v[76:79], v[190:193], v[174:177], v[76:79]
	v_mfma_f32_16x16x32_bf16 v[72:75], v[198:201], v[174:177], v[72:75]
	v_mfma_f32_16x16x32_bf16 v[68:71], v[190:193], v[182:185], v[68:71]
	s_setprio 0
	v_mfma_f32_16x16x32_bf16 v[64:67], v[198:201], v[182:185], v[64:67]
	s_barrier
; #define PG8_STAGE(bufoff, gbase, voff) do { _Pragma("unroll") for (int _i = 0; _i < 2; ++_i) \
;         __builtin_amdgcn_global_load_lds((const unsigned*)((const char*)(gbase) + (voff)[_i]), (LAS unsigned*)(lds + (bufoff) + ldsw + _i * 8192), 16, 0, 0); } while (0)
; #define PG8_LDA(dst, b, h) do { _Pragma("unroll") for (int m = 0; m < 4; ++m) _Pragma("unroll") for (int k = 0; k < 2; ++k) dst[m][k] = *(const LAS bf16x8*)(lds + PG8_SA(b, h) + aoff + m * 2048 + k * 1024); } while (0)
; #define PG8_WAIT_V(n) asm volatile("s_waitcnt vmcnt(" #n ")" ::: "memory")
; #define PG8_WAIT_L(n) asm volatile("s_waitcnt lgkmcnt(" #n ")" ::: "memory")
; template <class Epi>
; __device__ __forceinline__ void gemm_phase(LAS unsigned char* lds, const Gemm g, const StaticOrder& S, const Epi& E) {
;     ...
;         for (int t = 0; t < nt; t += 2) {
;             const bool last = (t == nt - 2);
;             const char* a1 = cA + (size_t)(t + 1) * kstep;
;             const char* a2 = last ? nA : cA + (size_t)(t + 2) * kstep; const char* b2 = last ? nB : cB + (size_t)(t + 2) * kstep;
;             const char* a3 = a2 + kstep; const char* b3 = b2 + kstep;
;             PG8_LDB(B0, 0, 0); PG8_SCHED; PG8_LDA(At, 0, 0); PG8_STAGE(PG8_SA(1, 1), a1 + hstepA, voffA);
;             PG8_WAIT_L(8); PG8_BAR; PG8_WAIT_L(0); PG8_MMA(0, 0, At, B0); PG8_BAR; PG8_SCHED;
;             PG8_LDB(B1, 0, 1); PG8_STAGE(PG8_SB(0, 0), b2, voffB);
;             PG8_BAR; PG8_WAIT_L(0); PG8_MMA(0, 1, At, B1); PG8_BAR;
;             PG8_LDA(At, 0, 1); PG8_STAGE(PG8_SA(0, 0), a2, voffA);
;             PG8_BAR; PG8_WAIT_L(0); PG8_MMA(1, 0, At, B0); PG8_BAR; PG8_SCHED;
;             PG8_STAGE(PG8_SB(0, 1), b2 + hstepB, voffB);
;             PG8_WAIT_V(6); PG8_BAR; PG8_MMA(1, 1, At, B1); PG8_BAR;
;             PG8_LDB(B0, 1, 0); PG8_SCHED; PG8_LDA(At, 1, 0); PG8_STAGE(PG8_SA(0, 1), a2 + hstepA, voffA);
;             PG8_WAIT_L(8); PG8_BAR; PG8_WAIT_L(0); PG8_MMA(0, 0, At, B0); PG8_BAR; PG8_SCHED;
;             PG8_LDB(B1, 1, 1); PG8_STAGE(PG8_SB(1, 0), b3, voffB);
;             PG8_BAR; PG8_WAIT_L(0); PG8_MMA(0, 1, At, B1); PG8_BAR;
;             PG8_LDA(At, 1, 1); PG8_STAGE(PG8_SA(1, 0), a3, voffA);
;             PG8_BAR; PG8_WAIT_L(0); PG8_MMA(1, 0, At, B0); PG8_BAR; PG8_SCHED;
;             PG8_STAGE(PG8_SB(1, 1), b3 + hstepB, voffB);
;             PG8_WAIT_V(6); PG8_BAR; PG8_MMA(1, 1, At, B1); PG8_BAR;
	s_mov_b32 m0, s27
	v_lshl_add_u64 v[202:203], s[24:25], 0, v[152:153]
	global_load_lds_dwordx4 v[202:203], off
	s_add_i32 m0, s27, 0x2000
	v_lshl_add_u64 v[202:203], s[24:25], 0, v[156:157]
	global_load_lds_dwordx4 v[202:203], off
	s_mov_b32 m0, s38
	v_lshl_add_u64 v[202:203], s[22:23], 0, v[152:153]
	global_load_lds_dwordx4 v[202:203], off nt
	s_mov_b32 m0, s39
	v_lshl_add_u64 v[202:203], s[22:23], 0, v[156:157]
	global_load_lds_dwordx4 v[202:203], off nt
	s_add_u32 s22, s24, s52
	s_addc_u32 s23, s25, 0
	s_add_i32 s24, s26, s31
	s_mov_b32 m0, s24
	v_lshl_add_u64 v[202:203], s[22:23], 0, v[152:153]
	global_load_lds_dwordx4 v[202:203], off
	s_add_i32 m0, s24, 0x2000
	v_lshl_add_u64 v[202:203], s[22:23], 0, v[156:157]
	global_load_lds_dwordx4 v[202:203], off
	ds_read_b128 v[144:147], v209 offset:49152
	ds_read_b128 v[162:165], v209 offset:51200
	ds_read_b128 v[170:173], v209 offset:53248
	ds_read_b128 v[178:181], v209 offset:55296
	ds_read_b128 v[148:151], v209 offset:50176
	ds_read_b128 v[166:169], v209 offset:52224
	ds_read_b128 v[174:177], v209 offset:54272
	ds_read_b128 v[182:185], v209 offset:56320
	s_waitcnt vmcnt(8)
	s_waitcnt lgkmcnt(0)
	s_barrier
	v_mfma_f32_16x16x32_bf16 v[60:63], v[128:131], v[144:147], v[60:63]
	s_setprio 1
	v_mfma_f32_16x16x32_bf16 v[56:59], v[136:139], v[144:147], v[56:59]
	v_mfma_f32_16x16x32_bf16 v[52:55], v[128:131], v[162:165], v[52:55]
	v_mfma_f32_16x16x32_bf16 v[48:51], v[136:139], v[162:165], v[48:51]
	v_mfma_f32_16x16x32_bf16 v[44:47], v[128:131], v[170:173], v[44:47]
	v_mfma_f32_16x16x32_bf16 v[40:43], v[136:139], v[170:173], v[40:43]
	v_mfma_f32_16x16x32_bf16 v[36:39], v[128:131], v[178:181], v[36:39]
	v_mfma_f32_16x16x32_bf16 v[32:35], v[136:139], v[178:181], v[32:35]
	v_mfma_f32_16x16x32_bf16 v[60:63], v[132:135], v[148:151], v[60:63]
	v_mfma_f32_16x16x32_bf16 v[56:59], v[140:143], v[148:151], v[56:59]
	v_mfma_f32_16x16x32_bf16 v[52:55], v[132:135], v[166:169], v[52:55]
	v_mfma_f32_16x16x32_bf16 v[48:51], v[140:143], v[166:169], v[48:51]
	v_mfma_f32_16x16x32_bf16 v[44:47], v[132:135], v[174:177], v[44:47]
	v_mfma_f32_16x16x32_bf16 v[40:43], v[140:143], v[174:177], v[40:43]
	v_mfma_f32_16x16x32_bf16 v[36:39], v[132:135], v[182:185], v[36:39]
	v_mfma_f32_16x16x32_bf16 v[32:35], v[140:143], v[182:185], v[32:35]
	v_mfma_f32_16x16x32_bf16 v[28:31], v[186:189], v[144:147], v[28:31]
	v_mfma_f32_16x16x32_bf16 v[24:27], v[194:197], v[144:147], v[24:27]
	s_add_u32 s4, s4, 0x8000
	s_addc_u32 s5, s5, 0
	s_add_u32 s50, s50, 0x8000
	s_addc_u32 s51, s51, 0
	v_mfma_f32_16x16x32_bf16 v[20:23], v[186:189], v[162:165], v[20:23]
	v_mfma_f32_16x16x32_bf16 v[16:19], v[194:197], v[162:165], v[16:19]
	v_mfma_f32_16x16x32_bf16 v[12:15], v[186:189], v[170:173], v[12:15]
	v_mfma_f32_16x16x32_bf16 v[8:11], v[194:197], v[170:173], v[8:11]
	v_mfma_f32_16x16x32_bf16 v[4:7], v[186:189], v[178:181], v[4:7]
	v_mfma_f32_16x16x32_bf16 v[0:3], v[194:197], v[178:181], v[0:3]
	v_mfma_f32_16x16x32_bf16 v[28:31], v[190:193], v[148:151], v[28:31]
	v_mfma_f32_16x16x32_bf16 v[24:27], v[198:201], v[148:151], v[24:27]
	v_mfma_f32_16x16x32_bf16 v[20:23], v[190:193], v[166:169], v[20:23]
	v_mfma_f32_16x16x32_bf16 v[16:19], v[198:201], v[166:169], v[16:19]
	v_mfma_f32_16x16x32_bf16 v[12:15], v[190:193], v[174:177], v[12:15]
	v_mfma_f32_16x16x32_bf16 v[8:11], v[198:201], v[174:177], v[8:11]
	v_mfma_f32_16x16x32_bf16 v[4:7], v[190:193], v[182:185], v[4:7]
	s_cmp_ge_u32 s54, s28
	s_mov_b32 s22, s54
	s_setprio 0
	v_mfma_f32_16x16x32_bf16 v[0:3], v[198:201], v[182:185], v[0:3]
	s_barrier
	s_cbranch_scc0 .LBB0_187
	s_branch .Lpeel_done_187
.LBB0_187:
	s_add_i32 s54, s22, 2
	s_add_u32 s23, s4, 0x4000
	s_addc_u32 s24, s5, 0
	s_cmp_eq_u32 s40, s22
	s_cselect_b32 s26, s6, s23
	s_cselect_b32 s27, s7, s24
	s_cselect_b32 s24, s20, s50
	s_cselect_b32 s25, s21, s51
	s_add_u32 s22, s26, 0x4000
	s_addc_u32 s23, s27, 0
	s_add_i32 m0, s33, 0xc000
	v_lshl_add_u64 v[186:187], s[4:5], 0, v[158:159]
	global_load_lds_dwordx4 v[186:187], off nt
	s_add_i32 m0, s33, 0xe000
	v_lshl_add_u64 v[186:187], s[4:5], 0, v[160:161]
	global_load_lds_dwordx4 v[186:187], off nt
	s_mov_b32 s55, 0x10000
	v_add_u32_e32 v140, s55, v207
	ds_read_b128 v[128:131], v140
	ds_read_b128 v[136:139], v140 offset:2048
	ds_read_b128 v[132:135], v140 offset:1024
	ds_read_b128 v[140:143], v140 offset:3072
	ds_read_b128 v[144:147], v209
	ds_read_b128 v[162:165], v209 offset:2048
	ds_read_b128 v[170:173], v209 offset:4096
	ds_read_b128 v[178:181], v209 offset:6144
	ds_read_b128 v[148:151], v209 offset:1024
	ds_read_b128 v[166:169], v209 offset:3072
	ds_read_b128 v[174:177], v209 offset:5120
	ds_read_b128 v[182:185], v209 offset:7168
	s_mov_b32 s58, 0x14000
	s_add_i32 s55, s55, s31
	v_add_u32_e32 v198, s58, v207
	ds_read_b128 v[186:189], v198
	ds_read_b128 v[194:197], v198 offset:2048
	ds_read_b128 v[190:193], v198 offset:1024
	ds_read_b128 v[198:201], v198 offset:3072
	s_waitcnt vmcnt(8)
	s_waitcnt lgkmcnt(0)
	s_barrier
; #define PG8_STAGE(bufoff, gbase, voff) do { _Pragma("unroll") for (int _i = 0; _i < 2; ++_i) \
;         __builtin_amdgcn_global_load_lds((const unsigned*)((const char*)(gbase) + (voff)[_i]), (LAS unsigned*)(lds + (bufoff) + ldsw + _i * 8192), 16, 0, 0); } while (0)
; #define PG8_LDA(dst, b, h) do { _Pragma("unroll") for (int m = 0; m < 4; ++m) _Pragma("unroll") for (int k = 0; k < 2; ++k) dst[m][k] = *(const LAS bf16x8*)(lds + PG8_SA(b, h) + aoff + m * 2048 + k * 1024); } while (0)
; #define PG8_LDB(dst, b, h) do { _Pragma("unroll") for (int n = 0; n < 2; ++n) _Pragma("unroll") for (int k = 0; k < 2; ++k) dst[n][k] = *(const LAS bf16x8*)(lds + PG8_SB(b, h) + boff + n * 2048 + k * 1024); } while (0)
; #define PG8_WAIT_V(n) asm volatile("s_waitcnt vmcnt(" #n ")" ::: "memory")
; #define PG8_WAIT_L(n) asm volatile("s_waitcnt lgkmcnt(" #n ")" ::: "memory")
; #define PG8_BAR __builtin_amdgcn_s_barrier()
; #define PG8_SCHED __builtin_amdgcn_sched_barrier(0)
; template <class Epi>
; __device__ __forceinline__ void gemm_phase(LAS unsigned char* lds, const Gemm g, const StaticOrder& S, const Epi& E) {
;     ...
;             PG8_LDB(B0, 0, 0); PG8_SCHED; PG8_LDA(At, 0, 0); PG8_STAGE(PG8_SA(1, 1), a1 + hstepA, voffA);
;             PG8_WAIT_L(8); PG8_BAR; PG8_WAIT_L(0); PG8_MMA(0, 0, At, B0); PG8_BAR; PG8_SCHED;
;             PG8_LDB(B1, 0, 1); PG8_STAGE(PG8_SB(0, 0), b2, voffB);
;             PG8_BAR; PG8_WAIT_L(0); PG8_MMA(0, 1, At, B1); PG8_BAR;
;             PG8_LDA(At, 0, 1); PG8_STAGE(PG8_SA(0, 0), a2, voffA);
;             PG8_BAR; PG8_WAIT_L(0); PG8_MMA(1, 0, At, B0); PG8_BAR; PG8_SCHED;
;             PG8_STAGE(PG8_SB(0, 1), b2 + hstepB, voffB);
;             PG8_WAIT_V(6); PG8_BAR; PG8_MMA(1, 1, At, B1); PG8_BAR;
;             PG8_LDB(B0, 1, 0); PG8_SCHED; PG8_LDA(At, 1, 0); PG8_STAGE(PG8_SA(0, 1), a2 + hstepA, voffA);
;             PG8_WAIT_L(8); PG8_BAR; PG8_WAIT_L(0); PG8_MMA(0, 0, At, B0); PG8_BAR; PG8_SCHED;
;             PG8_LDB(B1, 1, 1); PG8_STAGE(PG8_SB(1, 0), b3, voffB);
;             PG8_BAR; PG8_WAIT_L(0); PG8_MMA(0, 1, At, B1); PG8_BAR;
;             PG8_LDA(At, 1, 1); PG8_STAGE(PG8_SA(1, 0), a3, voffA);
;             PG8_BAR; PG8_WAIT_L(0); PG8_MMA(1, 0, At, B0); PG8_BAR; PG8_SCHED;
;             PG8_STAGE(PG8_SB(1, 1), b3 + hstepB, voffB);
;             PG8_WAIT_V(6); PG8_BAR; PG8_MMA(1, 1, At, B1); PG8_BAR;
	v_mfma_f32_16x16x32_bf16 v[124:127], v[128:131], v[144:147], v[124:127]
	s_setprio 1
	v_mfma_f32_16x16x32_bf16 v[120:123], v[136:139], v[144:147], v[120:123]
	v_mfma_f32_16x16x32_bf16 v[116:119], v[128:131], v[162:165], v[116:119]
	v_mfma_f32_16x16x32_bf16 v[112:115], v[136:139], v[162:165], v[112:115]
	v_mfma_f32_16x16x32_bf16 v[108:111], v[128:131], v[170:173], v[108:111]
	v_mfma_f32_16x16x32_bf16 v[104:107], v[136:139], v[170:173], v[104:107]
	v_mfma_f32_16x16x32_bf16 v[100:103], v[128:131], v[178:181], v[100:103]
	v_mfma_f32_16x16x32_bf16 v[96:99], v[136:139], v[178:181], v[96:99]
	v_mfma_f32_16x16x32_bf16 v[124:127], v[132:135], v[148:151], v[124:127]
	v_mfma_f32_16x16x32_bf16 v[120:123], v[140:143], v[148:151], v[120:123]
	v_mfma_f32_16x16x32_bf16 v[116:119], v[132:135], v[166:169], v[116:119]
	v_mfma_f32_16x16x32_bf16 v[112:115], v[140:143], v[166:169], v[112:115]
	v_mfma_f32_16x16x32_bf16 v[108:111], v[132:135], v[174:177], v[108:111]
	v_mfma_f32_16x16x32_bf16 v[104:107], v[140:143], v[174:177], v[104:107]
	v_mfma_f32_16x16x32_bf16 v[100:103], v[132:135], v[182:185], v[100:103]
	v_mfma_f32_16x16x32_bf16 v[96:99], v[140:143], v[182:185], v[96:99]
	v_mfma_f32_16x16x32_bf16 v[92:95], v[186:189], v[144:147], v[92:95]
	v_mfma_f32_16x16x32_bf16 v[88:91], v[194:197], v[144:147], v[88:91]
	v_mfma_f32_16x16x32_bf16 v[84:87], v[186:189], v[162:165], v[84:87]
	v_mfma_f32_16x16x32_bf16 v[80:83], v[194:197], v[162:165], v[80:83]
	v_mfma_f32_16x16x32_bf16 v[76:79], v[186:189], v[170:173], v[76:79]
	v_mfma_f32_16x16x32_bf16 v[72:75], v[194:197], v[170:173], v[72:75]
	v_mfma_f32_16x16x32_bf16 v[68:71], v[186:189], v[178:181], v[68:71]
	v_mfma_f32_16x16x32_bf16 v[64:67], v[194:197], v[178:181], v[64:67]
	v_mfma_f32_16x16x32_bf16 v[92:95], v[190:193], v[148:151], v[92:95]
	v_mfma_f32_16x16x32_bf16 v[88:91], v[198:201], v[148:151], v[88:91]
	v_mfma_f32_16x16x32_bf16 v[84:87], v[190:193], v[166:169], v[84:87]
	v_mfma_f32_16x16x32_bf16 v[80:83], v[198:201], v[166:169], v[80:83]
	v_mfma_f32_16x16x32_bf16 v[76:79], v[190:193], v[174:177], v[76:79]
	v_mfma_f32_16x16x32_bf16 v[72:75], v[198:201], v[174:177], v[72:75]
	v_mfma_f32_16x16x32_bf16 v[68:71], v[190:193], v[182:185], v[68:71]
	s_setprio 0
	v_mfma_f32_16x16x32_bf16 v[64:67], v[198:201], v[182:185], v[64:67]
	s_barrier
	s_mov_b32 m0, s55
	v_lshl_add_u64 v[202:203], s[24:25], 0, v[152:153]
	global_load_lds_dwordx4 v[202:203], off
	s_add_i32 m0, s55, 0x2000
	v_lshl_add_u64 v[202:203], s[24:25], 0, v[156:157]
	global_load_lds_dwordx4 v[202:203], off
	s_mov_b32 m0, s33
	v_lshl_add_u64 v[202:203], s[26:27], 0, v[152:153]
	global_load_lds_dwordx4 v[202:203], off nt
	s_mov_b32 m0, s34
	v_lshl_add_u64 v[202:203], s[26:27], 0, v[156:157]
	global_load_lds_dwordx4 v[202:203], off nt
	s_add_u32 s56, s24, s52
	s_addc_u32 s57, s25, 0
	s_add_i32 s55, s58, s31
	s_mov_b32 m0, s55
	v_lshl_add_u64 v[202:203], s[56:57], 0, v[152:153]
	global_load_lds_dwordx4 v[202:203], off
	s_add_i32 m0, s55, 0x2000
	v_lshl_add_u64 v[202:203], s[56:57], 0, v[156:157]
	global_load_lds_dwordx4 v[202:203], off
	ds_read_b128 v[144:147], v209 offset:16384
	ds_read_b128 v[162:165], v209 offset:18432
	ds_read_b128 v[170:173], v209 offset:20480
	ds_read_b128 v[178:181], v209 offset:22528
	ds_read_b128 v[148:151], v209 offset:17408
	ds_read_b128 v[166:169], v209 offset:19456
	ds_read_b128 v[174:177], v209 offset:21504
	ds_read_b128 v[182:185], v209 offset:23552
	s_waitcnt vmcnt(8)
	s_waitcnt lgkmcnt(0)
	s_barrier
	v_mfma_f32_16x16x32_bf16 v[60:63], v[128:131], v[144:147], v[60:63]
	s_setprio 1
	v_mfma_f32_16x16x32_bf16 v[56:59], v[136:139], v[144:147], v[56:59]
	v_mfma_f32_16x16x32_bf16 v[52:55], v[128:131], v[162:165], v[52:55]
	v_mfma_f32_16x16x32_bf16 v[48:51], v[136:139], v[162:165], v[48:51]
	v_mfma_f32_16x16x32_bf16 v[44:47], v[128:131], v[170:173], v[44:47]
	v_mfma_f32_16x16x32_bf16 v[40:43], v[136:139], v[170:173], v[40:43]
	v_mfma_f32_16x16x32_bf16 v[36:39], v[128:131], v[178:181], v[36:39]
	v_mfma_f32_16x16x32_bf16 v[32:35], v[136:139], v[178:181], v[32:35]
	v_mfma_f32_16x16x32_bf16 v[60:63], v[132:135], v[148:151], v[60:63]
	v_mfma_f32_16x16x32_bf16 v[56:59], v[140:143], v[148:151], v[56:59]
	v_mfma_f32_16x16x32_bf16 v[52:55], v[132:135], v[166:169], v[52:55]
	v_mfma_f32_16x16x32_bf16 v[48:51], v[140:143], v[166:169], v[48:51]
	v_mfma_f32_16x16x32_bf16 v[44:47], v[132:135], v[174:177], v[44:47]
	v_mfma_f32_16x16x32_bf16 v[40:43], v[140:143], v[174:177], v[40:43]
	v_mfma_f32_16x16x32_bf16 v[36:39], v[132:135], v[182:185], v[36:39]
	v_mfma_f32_16x16x32_bf16 v[32:35], v[140:143], v[182:185], v[32:35]
	v_mfma_f32_16x16x32_bf16 v[28:31], v[186:189], v[144:147], v[28:31]
	v_mfma_f32_16x16x32_bf16 v[24:27], v[194:197], v[144:147], v[24:27]
	s_add_i32 s55, 0, 0x18000
	v_add_u32_e32 v140, s55, v207
	v_mfma_f32_16x16x32_bf16 v[20:23], v[186:189], v[162:165], v[20:23]
	v_mfma_f32_16x16x32_bf16 v[16:19], v[194:197], v[162:165], v[16:19]
	v_mfma_f32_16x16x32_bf16 v[12:15], v[186:189], v[170:173], v[12:15]
	v_mfma_f32_16x16x32_bf16 v[8:11], v[194:197], v[170:173], v[8:11]
	v_mfma_f32_16x16x32_bf16 v[4:7], v[186:189], v[178:181], v[4:7]
	v_mfma_f32_16x16x32_bf16 v[0:3], v[194:197], v[178:181], v[0:3]
	v_mfma_f32_16x16x32_bf16 v[28:31], v[190:193], v[148:151], v[28:31]
	v_mfma_f32_16x16x32_bf16 v[24:27], v[198:201], v[148:151], v[24:27]
	v_mfma_f32_16x16x32_bf16 v[20:23], v[190:193], v[166:169], v[20:23]
	v_mfma_f32_16x16x32_bf16 v[16:19], v[198:201], v[166:169], v[16:19]
	v_mfma_f32_16x16x32_bf16 v[12:15], v[190:193], v[174:177], v[12:15]
	v_mfma_f32_16x16x32_bf16 v[8:11], v[198:201], v[174:177], v[8:11]
	v_mfma_f32_16x16x32_bf16 v[4:7], v[190:193], v[182:185], v[4:7]
	s_setprio 0
	v_mfma_f32_16x16x32_bf16 v[0:3], v[198:201], v[182:185], v[0:3]
	s_barrier
; #define PG8_STAGE(bufoff, gbase, voff) do { _Pragma("unroll") for (int _i = 0; _i < 2; ++_i) \
;         __builtin_amdgcn_global_load_lds((const unsigned*)((const char*)(gbase) + (voff)[_i]), (LAS unsigned*)(lds + (bufoff) + ldsw + _i * 8192), 16, 0, 0); } while (0)
; #define PG8_LDA(dst, b, h) do { _Pragma("unroll") for (int m = 0; m < 4; ++m) _Pragma("unroll") for (int k = 0; k < 2; ++k) dst[m][k] = *(const LAS bf16x8*)(lds + PG8_SA(b, h) + aoff + m * 2048 + k * 1024); } while (0)
; #define PG8_LDB(dst, b, h) do { _Pragma("unroll") for (int n = 0; n < 2; ++n) _Pragma("unroll") for (int k = 0; k < 2; ++k) dst[n][k] = *(const LAS bf16x8*)(lds + PG8_SB(b, h) + boff + n * 2048 + k * 1024); } while (0)
; #define PG8_WAIT_V(n) asm volatile("s_waitcnt vmcnt(" #n ")" ::: "memory")
; #define PG8_WAIT_L(n) asm volatile("s_waitcnt lgkmcnt(" #n ")" ::: "memory")
; #define PG8_BAR __builtin_amdgcn_s_barrier()
; #define PG8_SCHED __builtin_amdgcn_sched_barrier(0)
; template <class Epi>
; __device__ __forceinline__ void gemm_phase(LAS unsigned char* lds, const Gemm g, const StaticOrder& S, const Epi& E) {
;     ...
;             PG8_LDB(B0, 0, 0); PG8_SCHED; PG8_LDA(At, 0, 0); PG8_STAGE(PG8_SA(1, 1), a1 + hstepA, voffA);
;             PG8_WAIT_L(8); PG8_BAR; PG8_WAIT_L(0); PG8_MMA(0, 0, At, B0); PG8_BAR; PG8_SCHED;
;             PG8_LDB(B1, 0, 1); PG8_STAGE(PG8_SB(0, 0), b2, voffB);
;             PG8_BAR; PG8_WAIT_L(0); PG8_MMA(0, 1, At, B1); PG8_BAR;
;             PG8_LDA(At, 0, 1); PG8_STAGE(PG8_SA(0, 0), a2, voffA);
;             PG8_BAR; PG8_WAIT_L(0); PG8_MMA(1, 0, At, B0); PG8_BAR; PG8_SCHED;
;             PG8_STAGE(PG8_SB(0, 1), b2 + hstepB, voffB);
;             PG8_WAIT_V(6); PG8_BAR; PG8_MMA(1, 1, At, B1); PG8_BAR;
;             PG8_LDB(B0, 1, 0); PG8_SCHED; PG8_LDA(At, 1, 0); PG8_STAGE(PG8_SA(0, 1), a2 + hstepA, voffA);
;             PG8_WAIT_L(8); PG8_BAR; PG8_WAIT_L(0); PG8_MMA(0, 0, At, B0); PG8_BAR; PG8_SCHED;
;             PG8_LDB(B1, 1, 1); PG8_STAGE(PG8_SB(1, 0), b3, voffB);
;             PG8_BAR; PG8_WAIT_L(0); PG8_MMA(0, 1, At, B1); PG8_BAR;
;             PG8_LDA(At, 1, 1); PG8_STAGE(PG8_SA(1, 0), a3, voffA);
;             PG8_BAR; PG8_WAIT_L(0); PG8_MMA(1, 0, At, B0); PG8_BAR; PG8_SCHED;
;             PG8_STAGE(PG8_SB(1, 1), b3 + hstepB, voffB);
;             PG8_WAIT_V(6); PG8_BAR; PG8_MMA(1, 1, At, B1); PG8_BAR;
	s_add_u32 s26, s26, s52
	s_addc_u32 s27, s27, 0
	s_mov_b32 m0, s35
	v_lshl_add_u64 v[186:187], s[26:27], 0, v[152:153]
	global_load_lds_dwordx4 v[186:187], off nt
	s_mov_b32 m0, s36
	v_lshl_add_u64 v[186:187], s[26:27], 0, v[156:157]
	global_load_lds_dwordx4 v[186:187], off nt
	ds_read_b128 v[128:131], v140
	ds_read_b128 v[136:139], v140 offset:2048
	ds_read_b128 v[132:135], v140 offset:1024
	ds_read_b128 v[140:143], v140 offset:3072
	ds_read_b128 v[144:147], v209 offset:32768
	ds_read_b128 v[162:165], v209 offset:34816
	ds_read_b128 v[170:173], v209 offset:36864
	ds_read_b128 v[178:181], v209 offset:38912
	ds_read_b128 v[148:151], v209 offset:33792
	ds_read_b128 v[166:169], v209 offset:35840
	ds_read_b128 v[174:177], v209 offset:37888
	ds_read_b128 v[182:185], v209 offset:39936
	s_mov_b32 s26, 0x1c000
	s_add_u32 s24, s24, 0x4000
	s_addc_u32 s25, s25, 0
	s_add_i32 s27, s55, s31
	v_add_u32_e32 v198, s26, v207
	ds_read_b128 v[186:189], v198
	ds_read_b128 v[194:197], v198 offset:2048
	ds_read_b128 v[190:193], v198 offset:1024
	ds_read_b128 v[198:201], v198 offset:3072
	s_waitcnt vmcnt(8)
	s_waitcnt lgkmcnt(0)
	s_barrier
	v_mfma_f32_16x16x32_bf16 v[124:127], v[128:131], v[144:147], v[124:127]
	s_setprio 1
	v_mfma_f32_16x16x32_bf16 v[120:123], v[136:139], v[144:147], v[120:123]
	v_mfma_f32_16x16x32_bf16 v[116:119], v[128:131], v[162:165], v[116:119]
	v_mfma_f32_16x16x32_bf16 v[112:115], v[136:139], v[162:165], v[112:115]
	v_mfma_f32_16x16x32_bf16 v[108:111], v[128:131], v[170:173], v[108:111]
	v_mfma_f32_16x16x32_bf16 v[104:107], v[136:139], v[170:173], v[104:107]
	v_mfma_f32_16x16x32_bf16 v[100:103], v[128:131], v[178:181], v[100:103]
	v_mfma_f32_16x16x32_bf16 v[96:99], v[136:139], v[178:181], v[96:99]
	v_mfma_f32_16x16x32_bf16 v[124:127], v[132:135], v[148:151], v[124:127]
	v_mfma_f32_16x16x32_bf16 v[120:123], v[140:143], v[148:151], v[120:123]
	v_mfma_f32_16x16x32_bf16 v[116:119], v[132:135], v[166:169], v[116:119]
	v_mfma_f32_16x16x32_bf16 v[112:115], v[140:143], v[166:169], v[112:115]
	v_mfma_f32_16x16x32_bf16 v[108:111], v[132:135], v[174:177], v[108:111]
	v_mfma_f32_16x16x32_bf16 v[104:107], v[140:143], v[174:177], v[104:107]
	v_mfma_f32_16x16x32_bf16 v[100:103], v[132:135], v[182:185], v[100:103]
	v_mfma_f32_16x16x32_bf16 v[96:99], v[140:143], v[182:185], v[96:99]
	v_mfma_f32_16x16x32_bf16 v[92:95], v[186:189], v[144:147], v[92:95]
	v_mfma_f32_16x16x32_bf16 v[88:91], v[194:197], v[144:147], v[88:91]
	v_mfma_f32_16x16x32_bf16 v[84:87], v[186:189], v[162:165], v[84:87]
	v_mfma_f32_16x16x32_bf16 v[80:83], v[194:197], v[162:165], v[80:83]
	v_mfma_f32_16x16x32_bf16 v[76:79], v[186:189], v[170:173], v[76:79]
	v_mfma_f32_16x16x32_bf16 v[72:75], v[194:197], v[170:173], v[72:75]
	v_mfma_f32_16x16x32_bf16 v[68:71], v[186:189], v[178:181], v[68:71]
	v_mfma_f32_16x16x32_bf16 v[64:67], v[194:197], v[178:181], v[64:67]
	v_mfma_f32_16x16x32_bf16 v[92:95], v[190:193], v[148:151], v[92:95]
	v_mfma_f32_16x16x32_bf16 v[88:91], v[198:201], v[148:151], v[88:91]
	v_mfma_f32_16x16x32_bf16 v[84:87], v[190:193], v[166:169], v[84:87]
	v_mfma_f32_16x16x32_bf16 v[80:83], v[198:201], v[166:169], v[80:83]
	v_mfma_f32_16x16x32_bf16 v[76:79], v[190:193], v[174:177], v[76:79]
	v_mfma_f32_16x16x32_bf16 v[72:75], v[198:201], v[174:177], v[72:75]
	v_mfma_f32_16x16x32_bf16 v[68:71], v[190:193], v[182:185], v[68:71]
	s_setprio 0
	v_mfma_f32_16x16x32_bf16 v[64:67], v[198:201], v[182:185], v[64:67]
	s_barrier
	s_mov_b32 m0, s27
	v_lshl_add_u64 v[202:203], s[24:25], 0, v[152:153]
	global_load_lds_dwordx4 v[202:203], off
	s_add_i32 m0, s27, 0x2000
	v_lshl_add_u64 v[202:203], s[24:25], 0, v[156:157]
	global_load_lds_dwordx4 v[202:203], off
	s_mov_b32 m0, s38
	v_lshl_add_u64 v[202:203], s[22:23], 0, v[152:153]
	global_load_lds_dwordx4 v[202:203], off nt
	s_mov_b32 m0, s39
	v_lshl_add_u64 v[202:203], s[22:23], 0, v[156:157]
	global_load_lds_dwordx4 v[202:203], off nt
	s_add_u32 s22, s24, s52
	s_addc_u32 s23, s25, 0
	s_add_i32 s24, s26, s31
	s_mov_b32 m0, s24
	v_lshl_add_u64 v[202:203], s[22:23], 0, v[152:153]
	global_load_lds_dwordx4 v[202:203], off
	s_add_i32 m0, s24, 0x2000
	v_lshl_add_u64 v[202:203], s[22:23], 0, v[156:157]
	global_load_lds_dwordx4 v[202:203], off
	ds_read_b128 v[144:147], v209 offset:49152
	ds_read_b128 v[162:165], v209 offset:51200
	ds_read_b128 v[170:173], v209 offset:53248
	ds_read_b128 v[178:181], v209 offset:55296
	ds_read_b128 v[148:151], v209 offset:50176
	ds_read_b128 v[166:169], v209 offset:52224
	ds_read_b128 v[174:177], v209 offset:54272
	ds_read_b128 v[182:185], v209 offset:56320
	s_waitcnt vmcnt(8)
	s_waitcnt lgkmcnt(0)
	s_barrier
	v_mfma_f32_16x16x32_bf16 v[60:63], v[128:131], v[144:147], v[60:63]
	s_setprio 1
	v_mfma_f32_16x16x32_bf16 v[56:59], v[136:139], v[144:147], v[56:59]
	v_mfma_f32_16x16x32_bf16 v[52:55], v[128:131], v[162:165], v[52:55]
	v_mfma_f32_16x16x32_bf16 v[48:51], v[136:139], v[162:165], v[48:51]
	v_mfma_f32_16x16x32_bf16 v[44:47], v[128:131], v[170:173], v[44:47]
	v_mfma_f32_16x16x32_bf16 v[40:43], v[136:139], v[170:173], v[40:43]
	v_mfma_f32_16x16x32_bf16 v[36:39], v[128:131], v[178:181], v[36:39]
	v_mfma_f32_16x16x32_bf16 v[32:35], v[136:139], v[178:181], v[32:35]
	v_mfma_f32_16x16x32_bf16 v[60:63], v[132:135], v[148:151], v[60:63]
	v_mfma_f32_16x16x32_bf16 v[56:59], v[140:143], v[148:151], v[56:59]
	v_mfma_f32_16x16x32_bf16 v[52:55], v[132:135], v[166:169], v[52:55]
	v_mfma_f32_16x16x32_bf16 v[48:51], v[140:143], v[166:169], v[48:51]
	v_mfma_f32_16x16x32_bf16 v[44:47], v[132:135], v[174:177], v[44:47]
	v_mfma_f32_16x16x32_bf16 v[40:43], v[140:143], v[174:177], v[40:43]
	v_mfma_f32_16x16x32_bf16 v[36:39], v[132:135], v[182:185], v[36:39]
	v_mfma_f32_16x16x32_bf16 v[32:35], v[140:143], v[182:185], v[32:35]
	v_mfma_f32_16x16x32_bf16 v[28:31], v[186:189], v[144:147], v[28:31]
	v_mfma_f32_16x16x32_bf16 v[24:27], v[194:197], v[144:147], v[24:27]
	s_add_u32 s4, s4, 0x8000
	s_addc_u32 s5, s5, 0
	s_add_u32 s50, s50, 0x8000
	s_addc_u32 s51, s51, 0
	v_mfma_f32_16x16x32_bf16 v[20:23], v[186:189], v[162:165], v[20:23]
	v_mfma_f32_16x16x32_bf16 v[16:19], v[194:197], v[162:165], v[16:19]
	v_mfma_f32_16x16x32_bf16 v[12:15], v[186:189], v[170:173], v[12:15]
	v_mfma_f32_16x16x32_bf16 v[8:11], v[194:197], v[170:173], v[8:11]
	v_mfma_f32_16x16x32_bf16 v[4:7], v[186:189], v[178:181], v[4:7]
	v_mfma_f32_16x16x32_bf16 v[0:3], v[194:197], v[178:181], v[0:3]
	v_mfma_f32_16x16x32_bf16 v[28:31], v[190:193], v[148:151], v[28:31]
	v_mfma_f32_16x16x32_bf16 v[24:27], v[198:201], v[148:151], v[24:27]
	v_mfma_f32_16x16x32_bf16 v[20:23], v[190:193], v[166:169], v[20:23]
	v_mfma_f32_16x16x32_bf16 v[16:19], v[198:201], v[166:169], v[16:19]
	v_mfma_f32_16x16x32_bf16 v[12:15], v[190:193], v[174:177], v[12:15]
	v_mfma_f32_16x16x32_bf16 v[8:11], v[198:201], v[174:177], v[8:11]
	v_mfma_f32_16x16x32_bf16 v[4:7], v[190:193], v[182:185], v[4:7]
	s_cmp_ge_u32 s54, s28
	s_mov_b32 s22, s54
	s_setprio 0
	v_mfma_f32_16x16x32_bf16 v[0:3], v[198:201], v[182:185], v[0:3]
	s_barrier
	s_cbranch_scc0 .LBB0_187

; #define PG8_STAGE(bufoff, gbase, voff) do { _Pragma("unroll") for (int _i = 0; _i < 2; ++_i) \
;         __builtin_amdgcn_global_load_lds((const unsigned*)((const char*)(gbase) + (voff)[_i]), (LAS unsigned*)(lds + (bufoff) + ldsw + _i * 8192), 16, 0, 0); } while (0)
; #define PG8_LDA(dst, b, h) do { _Pragma("unroll") for (int m = 0; m < 4; ++m) _Pragma("unroll") for (int k = 0; k < 2; ++k) dst[m][k] = *(const LAS bf16x8*)(lds + PG8_SA(b, h) + aoff + m * 2048 + k * 1024); } while (0)
; #define PG8_LDB(dst, b, h) do { _Pragma("unroll") for (int n = 0; n < 2; ++n) _Pragma("unroll") for (int k = 0; k < 2; ++k) dst[n][k] = *(const LAS bf16x8*)(lds + PG8_SB(b, h) + boff + n * 2048 + k * 1024); } while (0)
; #define PG8_WAIT_V(n) asm volatile("s_waitcnt vmcnt(" #n ")" ::: "memory")
; #define PG8_WAIT_L(n) asm volatile("s_waitcnt lgkmcnt(" #n ")" ::: "memory")
; #define PG8_BAR __builtin_amdgcn_s_barrier()
; #define PG8_SCHED __builtin_amdgcn_sched_barrier(0)
; template <class Epi>
; __device__ __forceinline__ void gemm_phase(LAS unsigned char* lds, const Gemm g, const StaticOrder& S, const Epi& E) {
;     ...
;         const bool has_next = S.next(ui + 1, nxt);
;         const char* nA = has_next ? (const char*)g.A + (size_t)nxt.pm * tstepA : cA; const char* nB = has_next ? (const char*)g.Bt + (size_t)nxt.pn * tstepB : cB;
;         for (int t = 0; t < nt; t += 2) {
;             const bool last = (t == nt - 2);
;             const char* a1 = cA + (size_t)(t + 1) * kstep;
;             const char* a2 = last ? nA : cA + (size_t)(t + 2) * kstep; const char* b2 = last ? nB : cB + (size_t)(t + 2) * kstep;
;             const char* a3 = a2 + kstep; const char* b3 = b2 + kstep;
;             PG8_LDB(B0, 0, 0); PG8_SCHED; PG8_LDA(At, 0, 0); PG8_STAGE(PG8_SA(1, 1), a1 + hstepA, voffA);
;             PG8_WAIT_L(8); PG8_BAR; PG8_WAIT_L(0); PG8_MMA(0, 0, At, B0); PG8_BAR; PG8_SCHED;
;             PG8_LDB(B1, 0, 1); PG8_STAGE(PG8_SB(0, 0), b2, voffB);
;             PG8_BAR; PG8_WAIT_L(0); PG8_MMA(0, 1, At, B1); PG8_BAR;
;             PG8_LDA(At, 0, 1); PG8_STAGE(PG8_SA(0, 0), a2, voffA);
;             PG8_BAR; PG8_WAIT_L(0); PG8_MMA(1, 0, At, B0); PG8_BAR; PG8_SCHED;
;             PG8_STAGE(PG8_SB(0, 1), b2 + hstepB, voffB);
;             PG8_WAIT_V(6); PG8_BAR; PG8_MMA(1, 1, At, B1); PG8_BAR;
.LBB0_246:
	s_ashr_i32 s5, s4, 31
	v_cmp_lt_i64_e32 vcc, s[6:7], v[154:155]
	s_lshl_b64 s[6:7], s[4:5], 20
	v_readlane_b32 s8, v252, 53
	v_readlane_b32 s9, v252, 54
	s_add_u32 s6, s8, s6
	s_addc_u32 s7, s9, s7
	s_and_b64 s[8:9], vcc, exec
	s_cselect_b32 s5, s7, s13
	s_cselect_b32 s11, s6, s12
	s_ashr_i32 s3, s2, 31
	s_lshl_b64 s[8:9], s[2:3], 20
	s_add_u32 s8, s21, s8
	s_addc_u32 s9, s22, s9
	s_and_b64 s[16:17], vcc, exec
	s_cselect_b32 s3, s9, s15
	s_cselect_b32 s35, s8, s14
	s_add_u32 s12, s12, 0x84000
	s_addc_u32 s13, s13, 0
	s_add_u32 s36, s14, 0x8000
	s_addc_u32 s37, s15, 0
	s_mov_b32 s38, -2
	s_add_u32 s14, s12, 0xfff84000
	s_addc_u32 s15, s13, -1
	s_cmp_eq_u32 s38, 28
	s_cselect_b32 s18, s11, s14
	s_cselect_b32 s19, s5, s15
	s_cselect_b32 s14, s35, s36
	s_cselect_b32 s15, s3, s37
	s_add_u32 s16, s18, 0x4000
	s_addc_u32 s17, s19, 0
	s_add_i32 m0, s25, 0xc000
	v_lshl_add_u64 v[194:195], s[12:13], 0, v[156:157]
	global_load_lds_dwordx4 v[194:195], off
	s_add_i32 m0, s25, 0xe000
	v_lshl_add_u64 v[194:195], s[12:13], 0, v[158:159]
	global_load_lds_dwordx4 v[194:195], off
	s_mov_b32 s39, 0x10000
	v_add_u32_e32 v140, s39, v170
	ds_read_b128 v[128:131], v140
	ds_read_b128 v[136:139], v140 offset:2048
	ds_read_b128 v[132:135], v140 offset:1024
	ds_read_b128 v[140:143], v140 offset:3072
	ds_read_b128 v[144:147], v172
	ds_read_b128 v[166:169], v172 offset:2048
	ds_read_b128 v[178:181], v172 offset:4096
	ds_read_b128 v[186:189], v172 offset:6144
	ds_read_b128 v[148:151], v172 offset:1024
	ds_read_b128 v[174:177], v172 offset:3072
	ds_read_b128 v[182:185], v172 offset:5120
	ds_read_b128 v[190:193], v172 offset:7168
	s_mov_b32 s42, 0x14000
	s_add_i32 s39, s39, s23
	v_add_u32_e32 v152, s42, v170
	ds_read_b128 v[194:197], v152
	ds_read_b128 v[202:205], v152 offset:2048
	ds_read_b128 v[198:201], v152 offset:1024
	ds_read_b128 v[206:209], v152 offset:3072
	s_waitcnt vmcnt(8)
	s_waitcnt lgkmcnt(0)
	s_barrier
	v_mfma_f32_16x16x32_bf16 v[124:127], v[128:131], v[144:147], 0
	s_setprio 1
	v_mfma_f32_16x16x32_bf16 v[120:123], v[136:139], v[144:147], 0
	v_mfma_f32_16x16x32_bf16 v[108:111], v[128:131], v[166:169], 0
	v_mfma_f32_16x16x32_bf16 v[104:107], v[136:139], v[166:169], 0
	v_mfma_f32_16x16x32_bf16 v[92:95], v[128:131], v[178:181], 0
	v_mfma_f32_16x16x32_bf16 v[88:91], v[136:139], v[178:181], 0
	v_mfma_f32_16x16x32_bf16 v[76:79], v[128:131], v[186:189], 0
	v_mfma_f32_16x16x32_bf16 v[72:75], v[136:139], v[186:189], 0
	v_mfma_f32_16x16x32_bf16 v[124:127], v[132:135], v[148:151], v[124:127]
	v_mfma_f32_16x16x32_bf16 v[120:123], v[140:143], v[148:151], v[120:123]
	v_mfma_f32_16x16x32_bf16 v[108:111], v[132:135], v[174:177], v[108:111]
	v_mfma_f32_16x16x32_bf16 v[104:107], v[140:143], v[174:177], v[104:107]
	v_mfma_f32_16x16x32_bf16 v[92:95], v[132:135], v[182:185], v[92:95]
	v_mfma_f32_16x16x32_bf16 v[88:91], v[140:143], v[182:185], v[88:91]
	v_mfma_f32_16x16x32_bf16 v[76:79], v[132:135], v[190:193], v[76:79]
	v_mfma_f32_16x16x32_bf16 v[72:75], v[140:143], v[190:193], v[72:75]
	v_mfma_f32_16x16x32_bf16 v[116:119], v[194:197], v[144:147], 0
	v_mfma_f32_16x16x32_bf16 v[112:115], v[202:205], v[144:147], 0
	v_mfma_f32_16x16x32_bf16 v[100:103], v[194:197], v[166:169], 0
	v_mfma_f32_16x16x32_bf16 v[96:99], v[202:205], v[166:169], 0
	v_mfma_f32_16x16x32_bf16 v[84:87], v[194:197], v[178:181], 0
	v_mfma_f32_16x16x32_bf16 v[80:83], v[202:205], v[178:181], 0
	v_mfma_f32_16x16x32_bf16 v[68:71], v[194:197], v[186:189], 0
	v_mfma_f32_16x16x32_bf16 v[64:67], v[202:205], v[186:189], 0
	v_mfma_f32_16x16x32_bf16 v[116:119], v[198:201], v[148:151], v[116:119]
	v_mfma_f32_16x16x32_bf16 v[112:115], v[206:209], v[148:151], v[112:115]
	v_mfma_f32_16x16x32_bf16 v[100:103], v[198:201], v[174:177], v[100:103]
	v_mfma_f32_16x16x32_bf16 v[96:99], v[206:209], v[174:177], v[96:99]
	v_mfma_f32_16x16x32_bf16 v[84:87], v[198:201], v[182:185], v[84:87]
	v_mfma_f32_16x16x32_bf16 v[80:83], v[206:209], v[182:185], v[80:83]
	v_mfma_f32_16x16x32_bf16 v[68:71], v[198:201], v[190:193], v[68:71]
	s_setprio 0
	v_mfma_f32_16x16x32_bf16 v[64:67], v[206:209], v[190:193], v[64:67]
	s_barrier
	s_mov_b32 m0, s39
	v_lshl_add_u64 v[210:211], s[14:15], 0, v[156:157]
	global_load_lds_dwordx4 v[210:211], off
	s_add_i32 m0, s39, 0x2000
	v_lshl_add_u64 v[210:211], s[14:15], 0, v[158:159]
	global_load_lds_dwordx4 v[210:211], off
	s_mov_b32 m0, s25
	v_lshl_add_u64 v[210:211], s[18:19], 0, v[156:157]
	global_load_lds_dwordx4 v[210:211], off
	s_mov_b32 m0, s26
	v_lshl_add_u64 v[210:211], s[18:19], 0, v[158:159]
	global_load_lds_dwordx4 v[210:211], off
	s_add_u32 s40, s14, 0x80000
	s_addc_u32 s41, s15, 0
	s_add_i32 s39, s42, s23
	s_mov_b32 m0, s39
	v_lshl_add_u64 v[210:211], s[40:41], 0, v[156:157]
	global_load_lds_dwordx4 v[210:211], off
	s_add_i32 m0, s39, 0x2000
	v_lshl_add_u64 v[210:211], s[40:41], 0, v[158:159]
	global_load_lds_dwordx4 v[210:211], off
	ds_read_b128 v[144:147], v172 offset:16384
	ds_read_b128 v[166:169], v172 offset:18432
	ds_read_b128 v[178:181], v172 offset:20480
	ds_read_b128 v[186:189], v172 offset:22528
	ds_read_b128 v[148:151], v172 offset:17408
	ds_read_b128 v[174:177], v172 offset:19456
	ds_read_b128 v[182:185], v172 offset:21504
	ds_read_b128 v[190:193], v172 offset:23552
	s_waitcnt vmcnt(8)
	s_waitcnt lgkmcnt(0)
	s_barrier
; #define PG8_STAGE(bufoff, gbase, voff) do { _Pragma("unroll") for (int _i = 0; _i < 2; ++_i) \
;         __builtin_amdgcn_global_load_lds((const unsigned*)((const char*)(gbase) + (voff)[_i]), (LAS unsigned*)(lds + (bufoff) + ldsw + _i * 8192), 16, 0, 0); } while (0)
; #define PG8_LDA(dst, b, h) do { _Pragma("unroll") for (int m = 0; m < 4; ++m) _Pragma("unroll") for (int k = 0; k < 2; ++k) dst[m][k] = *(const LAS bf16x8*)(lds + PG8_SA(b, h) + aoff + m * 2048 + k * 1024); } while (0)
; #define PG8_LDB(dst, b, h) do { _Pragma("unroll") for (int n = 0; n < 2; ++n) _Pragma("unroll") for (int k = 0; k < 2; ++k) dst[n][k] = *(const LAS bf16x8*)(lds + PG8_SB(b, h) + boff + n * 2048 + k * 1024); } while (0)
; #define PG8_WAIT_V(n) asm volatile("s_waitcnt vmcnt(" #n ")" ::: "memory")
; #define PG8_WAIT_L(n) asm volatile("s_waitcnt lgkmcnt(" #n ")" ::: "memory")
; #define PG8_BAR __builtin_amdgcn_s_barrier()
; #define PG8_SCHED __builtin_amdgcn_sched_barrier(0)
; template <class Epi>
; __device__ __forceinline__ void gemm_phase(LAS unsigned char* lds, const Gemm g, const StaticOrder& S, const Epi& E) {
;     ...
;             PG8_LDB(B0, 0, 0); PG8_SCHED; PG8_LDA(At, 0, 0); PG8_STAGE(PG8_SA(1, 1), a1 + hstepA, voffA);
;             PG8_WAIT_L(8); PG8_BAR; PG8_WAIT_L(0); PG8_MMA(0, 0, At, B0); PG8_BAR; PG8_SCHED;
;             PG8_LDB(B1, 0, 1); PG8_STAGE(PG8_SB(0, 0), b2, voffB);
;             PG8_BAR; PG8_WAIT_L(0); PG8_MMA(0, 1, At, B1); PG8_BAR;
;             PG8_LDA(At, 0, 1); PG8_STAGE(PG8_SA(0, 0), a2, voffA);
;             PG8_BAR; PG8_WAIT_L(0); PG8_MMA(1, 0, At, B0); PG8_BAR; PG8_SCHED;
;             PG8_STAGE(PG8_SB(0, 1), b2 + hstepB, voffB);
;             PG8_WAIT_V(6); PG8_BAR; PG8_MMA(1, 1, At, B1); PG8_BAR;
;             PG8_LDB(B0, 1, 0); PG8_SCHED; PG8_LDA(At, 1, 0); PG8_STAGE(PG8_SA(0, 1), a2 + hstepA, voffA);
;             PG8_WAIT_L(8); PG8_BAR; PG8_WAIT_L(0); PG8_MMA(0, 0, At, B0); PG8_BAR; PG8_SCHED;
;             PG8_LDB(B1, 1, 1); PG8_STAGE(PG8_SB(1, 0), b3, voffB);
;             PG8_BAR; PG8_WAIT_L(0); PG8_MMA(0, 1, At, B1); PG8_BAR;
;             PG8_LDA(At, 1, 1); PG8_STAGE(PG8_SA(1, 0), a3, voffA);
;             PG8_BAR; PG8_WAIT_L(0); PG8_MMA(1, 0, At, B0); PG8_BAR; PG8_SCHED;
;             PG8_STAGE(PG8_SB(1, 1), b3 + hstepB, voffB);
;             PG8_WAIT_V(6); PG8_BAR; PG8_MMA(1, 1, At, B1); PG8_BAR;
	v_mfma_f32_16x16x32_bf16 v[60:63], v[128:131], v[144:147], 0
	s_setprio 1
	v_mfma_f32_16x16x32_bf16 v[56:59], v[136:139], v[144:147], 0
	v_mfma_f32_16x16x32_bf16 v[44:47], v[128:131], v[166:169], 0
	v_mfma_f32_16x16x32_bf16 v[40:43], v[136:139], v[166:169], 0
	v_mfma_f32_16x16x32_bf16 v[28:31], v[128:131], v[178:181], 0
	v_mfma_f32_16x16x32_bf16 v[24:27], v[136:139], v[178:181], 0
	v_mfma_f32_16x16x32_bf16 v[12:15], v[128:131], v[186:189], 0
	v_mfma_f32_16x16x32_bf16 v[8:11], v[136:139], v[186:189], 0
	v_mfma_f32_16x16x32_bf16 v[60:63], v[132:135], v[148:151], v[60:63]
	v_mfma_f32_16x16x32_bf16 v[56:59], v[140:143], v[148:151], v[56:59]
	v_mfma_f32_16x16x32_bf16 v[44:47], v[132:135], v[174:177], v[44:47]
	v_mfma_f32_16x16x32_bf16 v[40:43], v[140:143], v[174:177], v[40:43]
	v_mfma_f32_16x16x32_bf16 v[28:31], v[132:135], v[182:185], v[28:31]
	v_mfma_f32_16x16x32_bf16 v[24:27], v[140:143], v[182:185], v[24:27]
	v_mfma_f32_16x16x32_bf16 v[12:15], v[132:135], v[190:193], v[12:15]
	v_mfma_f32_16x16x32_bf16 v[8:11], v[140:143], v[190:193], v[8:11]
	v_mfma_f32_16x16x32_bf16 v[52:55], v[194:197], v[144:147], 0
	v_mfma_f32_16x16x32_bf16 v[48:51], v[202:205], v[144:147], 0
	s_add_i32 s39, 0, 0x18000
	v_add_u32_e32 v140, s39, v170
	v_mfma_f32_16x16x32_bf16 v[36:39], v[194:197], v[166:169], 0
	v_mfma_f32_16x16x32_bf16 v[32:35], v[202:205], v[166:169], 0
	v_mfma_f32_16x16x32_bf16 v[20:23], v[194:197], v[178:181], 0
	v_mfma_f32_16x16x32_bf16 v[16:19], v[202:205], v[178:181], 0
	v_mfma_f32_16x16x32_bf16 v[4:7], v[194:197], v[186:189], 0
	v_mfma_f32_16x16x32_bf16 v[0:3], v[202:205], v[186:189], 0
	v_mfma_f32_16x16x32_bf16 v[52:55], v[198:201], v[148:151], v[52:55]
	v_mfma_f32_16x16x32_bf16 v[48:51], v[206:209], v[148:151], v[48:51]
	v_mfma_f32_16x16x32_bf16 v[36:39], v[198:201], v[174:177], v[36:39]
	v_mfma_f32_16x16x32_bf16 v[32:35], v[206:209], v[174:177], v[32:35]
	v_mfma_f32_16x16x32_bf16 v[20:23], v[198:201], v[182:185], v[20:23]
	v_mfma_f32_16x16x32_bf16 v[16:19], v[206:209], v[182:185], v[16:19]
	v_mfma_f32_16x16x32_bf16 v[4:7], v[198:201], v[190:193], v[4:7]
	s_setprio 0
	v_mfma_f32_16x16x32_bf16 v[0:3], v[206:209], v[190:193], v[0:3]
	s_barrier
	s_add_u32 s18, s18, 0x80000
	s_addc_u32 s19, s19, 0
	s_mov_b32 m0, s27
	v_lshl_add_u64 v[194:195], s[18:19], 0, v[156:157]
	global_load_lds_dwordx4 v[194:195], off
	s_mov_b32 m0, s28
	v_lshl_add_u64 v[194:195], s[18:19], 0, v[158:159]
	global_load_lds_dwordx4 v[194:195], off
	ds_read_b128 v[128:131], v140
	ds_read_b128 v[136:139], v140 offset:2048
	ds_read_b128 v[132:135], v140 offset:1024
	ds_read_b128 v[140:143], v140 offset:3072
	ds_read_b128 v[144:147], v172 offset:32768
	ds_read_b128 v[166:169], v172 offset:34816
	ds_read_b128 v[178:181], v172 offset:36864
	ds_read_b128 v[186:189], v172 offset:38912
	ds_read_b128 v[148:151], v172 offset:33792
	ds_read_b128 v[174:177], v172 offset:35840
	ds_read_b128 v[182:185], v172 offset:37888
	ds_read_b128 v[190:193], v172 offset:39936
	s_mov_b32 s40, 0x1c000
	s_add_u32 s18, s14, 0x4000
	s_addc_u32 s19, s15, 0
	s_add_i32 s39, s39, s23
	v_add_u32_e32 v152, s40, v170
	ds_read_b128 v[194:197], v152
	ds_read_b128 v[202:205], v152 offset:2048
	ds_read_b128 v[198:201], v152 offset:1024
	ds_read_b128 v[206:209], v152 offset:3072
	s_waitcnt vmcnt(8)
	s_waitcnt lgkmcnt(0)
	s_barrier
	v_mfma_f32_16x16x32_bf16 v[124:127], v[128:131], v[144:147], v[124:127]
	s_setprio 1
	v_mfma_f32_16x16x32_bf16 v[120:123], v[136:139], v[144:147], v[120:123]
	v_mfma_f32_16x16x32_bf16 v[108:111], v[128:131], v[166:169], v[108:111]
	v_mfma_f32_16x16x32_bf16 v[104:107], v[136:139], v[166:169], v[104:107]
	v_mfma_f32_16x16x32_bf16 v[92:95], v[128:131], v[178:181], v[92:95]
	v_mfma_f32_16x16x32_bf16 v[88:91], v[136:139], v[178:181], v[88:91]
	v_mfma_f32_16x16x32_bf16 v[76:79], v[128:131], v[186:189], v[76:79]
	v_mfma_f32_16x16x32_bf16 v[72:75], v[136:139], v[186:189], v[72:75]
	v_mfma_f32_16x16x32_bf16 v[124:127], v[132:135], v[148:151], v[124:127]
	v_mfma_f32_16x16x32_bf16 v[120:123], v[140:143], v[148:151], v[120:123]
	v_mfma_f32_16x16x32_bf16 v[108:111], v[132:135], v[174:177], v[108:111]
	v_mfma_f32_16x16x32_bf16 v[104:107], v[140:143], v[174:177], v[104:107]
	v_mfma_f32_16x16x32_bf16 v[92:95], v[132:135], v[182:185], v[92:95]
	v_mfma_f32_16x16x32_bf16 v[88:91], v[140:143], v[182:185], v[88:91]
	v_mfma_f32_16x16x32_bf16 v[76:79], v[132:135], v[190:193], v[76:79]
	v_mfma_f32_16x16x32_bf16 v[72:75], v[140:143], v[190:193], v[72:75]
	v_mfma_f32_16x16x32_bf16 v[116:119], v[194:197], v[144:147], v[116:119]
	v_mfma_f32_16x16x32_bf16 v[112:115], v[202:205], v[144:147], v[112:115]
	v_mfma_f32_16x16x32_bf16 v[100:103], v[194:197], v[166:169], v[100:103]
	v_mfma_f32_16x16x32_bf16 v[96:99], v[202:205], v[166:169], v[96:99]
	v_mfma_f32_16x16x32_bf16 v[84:87], v[194:197], v[178:181], v[84:87]
	v_mfma_f32_16x16x32_bf16 v[80:83], v[202:205], v[178:181], v[80:83]
	v_mfma_f32_16x16x32_bf16 v[68:71], v[194:197], v[186:189], v[68:71]
	v_mfma_f32_16x16x32_bf16 v[64:67], v[202:205], v[186:189], v[64:67]
	v_mfma_f32_16x16x32_bf16 v[116:119], v[198:201], v[148:151], v[116:119]
	v_mfma_f32_16x16x32_bf16 v[112:115], v[206:209], v[148:151], v[112:115]
	v_mfma_f32_16x16x32_bf16 v[100:103], v[198:201], v[174:177], v[100:103]
	v_mfma_f32_16x16x32_bf16 v[96:99], v[206:209], v[174:177], v[96:99]
	v_mfma_f32_16x16x32_bf16 v[84:87], v[198:201], v[182:185], v[84:87]
	v_mfma_f32_16x16x32_bf16 v[80:83], v[206:209], v[182:185], v[80:83]
	v_mfma_f32_16x16x32_bf16 v[68:71], v[198:201], v[190:193], v[68:71]
	s_setprio 0
	v_mfma_f32_16x16x32_bf16 v[64:67], v[206:209], v[190:193], v[64:67]
	s_barrier
; #define PG8_STAGE(bufoff, gbase, voff) do { _Pragma("unroll") for (int _i = 0; _i < 2; ++_i) \
;         __builtin_amdgcn_global_load_lds((const unsigned*)((const char*)(gbase) + (voff)[_i]), (LAS unsigned*)(lds + (bufoff) + ldsw + _i * 8192), 16, 0, 0); } while (0)
; #define PG8_LDA(dst, b, h) do { _Pragma("unroll") for (int m = 0; m < 4; ++m) _Pragma("unroll") for (int k = 0; k < 2; ++k) dst[m][k] = *(const LAS bf16x8*)(lds + PG8_SA(b, h) + aoff + m * 2048 + k * 1024); } while (0)
; #define PG8_WAIT_V(n) asm volatile("s_waitcnt vmcnt(" #n ")" ::: "memory")
; #define PG8_WAIT_L(n) asm volatile("s_waitcnt lgkmcnt(" #n ")" ::: "memory")
; template <class Epi>
; __device__ __forceinline__ void gemm_phase(LAS unsigned char* lds, const Gemm g, const StaticOrder& S, const Epi& E) {
;     ...
;         for (int t = 0; t < nt; t += 2) {
;             const bool last = (t == nt - 2);
;             const char* a1 = cA + (size_t)(t + 1) * kstep;
;             const char* a2 = last ? nA : cA + (size_t)(t + 2) * kstep; const char* b2 = last ? nB : cB + (size_t)(t + 2) * kstep;
;             const char* a3 = a2 + kstep; const char* b3 = b2 + kstep;
;             PG8_LDB(B0, 0, 0); PG8_SCHED; PG8_LDA(At, 0, 0); PG8_STAGE(PG8_SA(1, 1), a1 + hstepA, voffA);
;             PG8_WAIT_L(8); PG8_BAR; PG8_WAIT_L(0); PG8_MMA(0, 0, At, B0); PG8_BAR; PG8_SCHED;
;             PG8_LDB(B1, 0, 1); PG8_STAGE(PG8_SB(0, 0), b2, voffB);
;             PG8_BAR; PG8_WAIT_L(0); PG8_MMA(0, 1, At, B1); PG8_BAR;
;             PG8_LDA(At, 0, 1); PG8_STAGE(PG8_SA(0, 0), a2, voffA);
;             PG8_BAR; PG8_WAIT_L(0); PG8_MMA(1, 0, At, B0); PG8_BAR; PG8_SCHED;
;             PG8_STAGE(PG8_SB(0, 1), b2 + hstepB, voffB);
;             PG8_WAIT_V(6); PG8_BAR; PG8_MMA(1, 1, At, B1); PG8_BAR;
;             PG8_LDB(B0, 1, 0); PG8_SCHED; PG8_LDA(At, 1, 0); PG8_STAGE(PG8_SA(0, 1), a2 + hstepA, voffA);
;             PG8_WAIT_L(8); PG8_BAR; PG8_WAIT_L(0); PG8_MMA(0, 0, At, B0); PG8_BAR; PG8_SCHED;
;             PG8_LDB(B1, 1, 1); PG8_STAGE(PG8_SB(1, 0), b3, voffB);
;             PG8_BAR; PG8_WAIT_L(0); PG8_MMA(0, 1, At, B1); PG8_BAR;
;             PG8_LDA(At, 1, 1); PG8_STAGE(PG8_SA(1, 0), a3, voffA);
;             PG8_BAR; PG8_WAIT_L(0); PG8_MMA(1, 0, At, B0); PG8_BAR; PG8_SCHED;
;             PG8_STAGE(PG8_SB(1, 1), b3 + hstepB, voffB);
;             PG8_WAIT_V(6); PG8_BAR; PG8_MMA(1, 1, At, B1); PG8_BAR;
	s_mov_b32 m0, s39
	v_lshl_add_u64 v[210:211], s[18:19], 0, v[156:157]
	global_load_lds_dwordx4 v[210:211], off
	s_add_i32 m0, s39, 0x2000
	v_lshl_add_u64 v[210:211], s[18:19], 0, v[158:159]
	global_load_lds_dwordx4 v[210:211], off
	s_mov_b32 m0, s29
	v_lshl_add_u64 v[210:211], s[16:17], 0, v[156:157]
	global_load_lds_dwordx4 v[210:211], off
	s_mov_b32 m0, s30
	v_lshl_add_u64 v[210:211], s[16:17], 0, v[158:159]
	global_load_lds_dwordx4 v[210:211], off
	s_add_u32 s14, s14, 0x84000
	s_addc_u32 s15, s15, 0
	s_add_i32 s16, s40, s23
	s_mov_b32 m0, s16
	v_lshl_add_u64 v[210:211], s[14:15], 0, v[156:157]
	global_load_lds_dwordx4 v[210:211], off
	s_add_i32 m0, s16, 0x2000
	v_lshl_add_u64 v[210:211], s[14:15], 0, v[158:159]
	global_load_lds_dwordx4 v[210:211], off
	ds_read_b128 v[144:147], v172 offset:49152
	ds_read_b128 v[166:169], v172 offset:51200
	ds_read_b128 v[178:181], v172 offset:53248
	ds_read_b128 v[186:189], v172 offset:55296
	ds_read_b128 v[148:151], v172 offset:50176
	ds_read_b128 v[174:177], v172 offset:52224
	ds_read_b128 v[182:185], v172 offset:54272
	ds_read_b128 v[190:193], v172 offset:56320
	s_waitcnt vmcnt(8)
	s_waitcnt lgkmcnt(0)
	s_barrier
	v_mfma_f32_16x16x32_bf16 v[60:63], v[128:131], v[144:147], v[60:63]
	s_setprio 1
	v_mfma_f32_16x16x32_bf16 v[56:59], v[136:139], v[144:147], v[56:59]
	v_mfma_f32_16x16x32_bf16 v[44:47], v[128:131], v[166:169], v[44:47]
	v_mfma_f32_16x16x32_bf16 v[40:43], v[136:139], v[166:169], v[40:43]
	v_mfma_f32_16x16x32_bf16 v[28:31], v[128:131], v[178:181], v[28:31]
	v_mfma_f32_16x16x32_bf16 v[24:27], v[136:139], v[178:181], v[24:27]
	v_mfma_f32_16x16x32_bf16 v[12:15], v[128:131], v[186:189], v[12:15]
	v_mfma_f32_16x16x32_bf16 v[8:11], v[136:139], v[186:189], v[8:11]
	v_mfma_f32_16x16x32_bf16 v[60:63], v[132:135], v[148:151], v[60:63]
	v_mfma_f32_16x16x32_bf16 v[56:59], v[140:143], v[148:151], v[56:59]
	v_mfma_f32_16x16x32_bf16 v[44:47], v[132:135], v[174:177], v[44:47]
	v_mfma_f32_16x16x32_bf16 v[40:43], v[140:143], v[174:177], v[40:43]
	v_mfma_f32_16x16x32_bf16 v[28:31], v[132:135], v[182:185], v[28:31]
	v_mfma_f32_16x16x32_bf16 v[24:27], v[140:143], v[182:185], v[24:27]
	v_mfma_f32_16x16x32_bf16 v[12:15], v[132:135], v[190:193], v[12:15]
	v_mfma_f32_16x16x32_bf16 v[8:11], v[140:143], v[190:193], v[8:11]
	v_mfma_f32_16x16x32_bf16 v[52:55], v[194:197], v[144:147], v[52:55]
	v_mfma_f32_16x16x32_bf16 v[48:51], v[202:205], v[144:147], v[48:51]
	s_add_i32 s38, s38, 2
	s_add_u32 s12, s12, 0x8000
	s_addc_u32 s13, s13, 0
	s_add_u32 s36, s36, 0x8000
	s_addc_u32 s37, s37, 0
	v_mfma_f32_16x16x32_bf16 v[36:39], v[194:197], v[166:169], v[36:39]
	v_mfma_f32_16x16x32_bf16 v[32:35], v[202:205], v[166:169], v[32:35]
	v_mfma_f32_16x16x32_bf16 v[20:23], v[194:197], v[178:181], v[20:23]
	v_mfma_f32_16x16x32_bf16 v[16:19], v[202:205], v[178:181], v[16:19]
	v_mfma_f32_16x16x32_bf16 v[4:7], v[194:197], v[186:189], v[4:7]
	v_mfma_f32_16x16x32_bf16 v[0:3], v[202:205], v[186:189], v[0:3]
	v_mfma_f32_16x16x32_bf16 v[52:55], v[198:201], v[148:151], v[52:55]
	v_mfma_f32_16x16x32_bf16 v[48:51], v[206:209], v[148:151], v[48:51]
	v_mfma_f32_16x16x32_bf16 v[36:39], v[198:201], v[174:177], v[36:39]
	v_mfma_f32_16x16x32_bf16 v[32:35], v[206:209], v[174:177], v[32:35]
	v_mfma_f32_16x16x32_bf16 v[20:23], v[198:201], v[182:185], v[20:23]
	v_mfma_f32_16x16x32_bf16 v[16:19], v[206:209], v[182:185], v[16:19]
	v_mfma_f32_16x16x32_bf16 v[4:7], v[198:201], v[190:193], v[4:7]
	s_cmp_gt_u32 s38, 29
	s_setprio 0
	v_mfma_f32_16x16x32_bf16 v[0:3], v[206:209], v[190:193], v[0:3]
	s_barrier
	s_cbranch_scc0 .LBB0_247
	s_branch .Lpeel_done_247
.LBB0_247:
	s_add_u32 s14, s12, 0xfff84000
	s_addc_u32 s15, s13, -1
	s_cmp_eq_u32 s38, 28
	s_cselect_b32 s18, s11, s14
	s_cselect_b32 s19, s5, s15
	s_cselect_b32 s14, s35, s36
	s_cselect_b32 s15, s3, s37
	s_add_u32 s16, s18, 0x4000
	s_addc_u32 s17, s19, 0
	s_add_i32 m0, s25, 0xc000
	v_lshl_add_u64 v[194:195], s[12:13], 0, v[156:157]
	global_load_lds_dwordx4 v[194:195], off
	s_add_i32 m0, s25, 0xe000
	v_lshl_add_u64 v[194:195], s[12:13], 0, v[158:159]
	global_load_lds_dwordx4 v[194:195], off
	s_mov_b32 s39, 0x10000
	v_add_u32_e32 v140, s39, v170
	ds_read_b128 v[128:131], v140
	ds_read_b128 v[136:139], v140 offset:2048
	ds_read_b128 v[132:135], v140 offset:1024
	ds_read_b128 v[140:143], v140 offset:3072
	ds_read_b128 v[144:147], v172
	ds_read_b128 v[166:169], v172 offset:2048
	ds_read_b128 v[178:181], v172 offset:4096
	ds_read_b128 v[186:189], v172 offset:6144
	ds_read_b128 v[148:151], v172 offset:1024
	ds_read_b128 v[174:177], v172 offset:3072
	ds_read_b128 v[182:185], v172 offset:5120
	ds_read_b128 v[190:193], v172 offset:7168
	s_mov_b32 s42, 0x14000
	s_add_i32 s39, s39, s23
	v_add_u32_e32 v152, s42, v170
	ds_read_b128 v[194:197], v152
	ds_read_b128 v[202:205], v152 offset:2048
	ds_read_b128 v[198:201], v152 offset:1024
	ds_read_b128 v[206:209], v152 offset:3072
	s_waitcnt vmcnt(8)
	s_waitcnt lgkmcnt(0)
	s_barrier
; #define PG8_STAGE(bufoff, gbase, voff) do { _Pragma("unroll") for (int _i = 0; _i < 2; ++_i) \
;         __builtin_amdgcn_global_load_lds((const unsigned*)((const char*)(gbase) + (voff)[_i]), (LAS unsigned*)(lds + (bufoff) + ldsw + _i * 8192), 16, 0, 0); } while (0)
; #define PG8_LDA(dst, b, h) do { _Pragma("unroll") for (int m = 0; m < 4; ++m) _Pragma("unroll") for (int k = 0; k < 2; ++k) dst[m][k] = *(const LAS bf16x8*)(lds + PG8_SA(b, h) + aoff + m * 2048 + k * 1024); } while (0)
; #define PG8_LDB(dst, b, h) do { _Pragma("unroll") for (int n = 0; n < 2; ++n) _Pragma("unroll") for (int k = 0; k < 2; ++k) dst[n][k] = *(const LAS bf16x8*)(lds + PG8_SB(b, h) + boff + n * 2048 + k * 1024); } while (0)
; #define PG8_WAIT_V(n) asm volatile("s_waitcnt vmcnt(" #n ")" ::: "memory")
; #define PG8_WAIT_L(n) asm volatile("s_waitcnt lgkmcnt(" #n ")" ::: "memory")
; #define PG8_BAR __builtin_amdgcn_s_barrier()
; #define PG8_SCHED __builtin_amdgcn_sched_barrier(0)
; template <class Epi>
; __device__ __forceinline__ void gemm_phase(LAS unsigned char* lds, const Gemm g, const StaticOrder& S, const Epi& E) {
;     ...
;             PG8_LDB(B0, 0, 0); PG8_SCHED; PG8_LDA(At, 0, 0); PG8_STAGE(PG8_SA(1, 1), a1 + hstepA, voffA);
;             PG8_WAIT_L(8); PG8_BAR; PG8_WAIT_L(0); PG8_MMA(0, 0, At, B0); PG8_BAR; PG8_SCHED;
;             PG8_LDB(B1, 0, 1); PG8_STAGE(PG8_SB(0, 0), b2, voffB);
;             PG8_BAR; PG8_WAIT_L(0); PG8_MMA(0, 1, At, B1); PG8_BAR;
;             PG8_LDA(At, 0, 1); PG8_STAGE(PG8_SA(0, 0), a2, voffA);
;             PG8_BAR; PG8_WAIT_L(0); PG8_MMA(1, 0, At, B0); PG8_BAR; PG8_SCHED;
;             PG8_STAGE(PG8_SB(0, 1), b2 + hstepB, voffB);
;             PG8_WAIT_V(6); PG8_BAR; PG8_MMA(1, 1, At, B1); PG8_BAR;
;             PG8_LDB(B0, 1, 0); PG8_SCHED; PG8_LDA(At, 1, 0); PG8_STAGE(PG8_SA(0, 1), a2 + hstepA, voffA);
;             PG8_WAIT_L(8); PG8_BAR; PG8_WAIT_L(0); PG8_MMA(0, 0, At, B0); PG8_BAR; PG8_SCHED;
;             PG8_LDB(B1, 1, 1); PG8_STAGE(PG8_SB(1, 0), b3, voffB);
;             PG8_BAR; PG8_WAIT_L(0); PG8_MMA(0, 1, At, B1); PG8_BAR;
;             PG8_LDA(At, 1, 1); PG8_STAGE(PG8_SA(1, 0), a3, voffA);
;             PG8_BAR; PG8_WAIT_L(0); PG8_MMA(1, 0, At, B0); PG8_BAR; PG8_SCHED;
;             PG8_STAGE(PG8_SB(1, 1), b3 + hstepB, voffB);
;             PG8_WAIT_V(6); PG8_BAR; PG8_MMA(1, 1, At, B1); PG8_BAR;
	v_mfma_f32_16x16x32_bf16 v[124:127], v[128:131], v[144:147], v[124:127]
	s_setprio 1
	v_mfma_f32_16x16x32_bf16 v[120:123], v[136:139], v[144:147], v[120:123]
	v_mfma_f32_16x16x32_bf16 v[108:111], v[128:131], v[166:169], v[108:111]
	v_mfma_f32_16x16x32_bf16 v[104:107], v[136:139], v[166:169], v[104:107]
	v_mfma_f32_16x16x32_bf16 v[92:95], v[128:131], v[178:181], v[92:95]
	v_mfma_f32_16x16x32_bf16 v[88:91], v[136:139], v[178:181], v[88:91]
	v_mfma_f32_16x16x32_bf16 v[76:79], v[128:131], v[186:189], v[76:79]
	v_mfma_f32_16x16x32_bf16 v[72:75], v[136:139], v[186:189], v[72:75]
	v_mfma_f32_16x16x32_bf16 v[124:127], v[132:135], v[148:151], v[124:127]
	v_mfma_f32_16x16x32_bf16 v[120:123], v[140:143], v[148:151], v[120:123]
	v_mfma_f32_16x16x32_bf16 v[108:111], v[132:135], v[174:177], v[108:111]
	v_mfma_f32_16x16x32_bf16 v[104:107], v[140:143], v[174:177], v[104:107]
	v_mfma_f32_16x16x32_bf16 v[92:95], v[132:135], v[182:185], v[92:95]
	v_mfma_f32_16x16x32_bf16 v[88:91], v[140:143], v[182:185], v[88:91]
	v_mfma_f32_16x16x32_bf16 v[76:79], v[132:135], v[190:193], v[76:79]
	v_mfma_f32_16x16x32_bf16 v[72:75], v[140:143], v[190:193], v[72:75]
	v_mfma_f32_16x16x32_bf16 v[116:119], v[194:197], v[144:147], v[116:119]
	v_mfma_f32_16x16x32_bf16 v[112:115], v[202:205], v[144:147], v[112:115]
	v_mfma_f32_16x16x32_bf16 v[100:103], v[194:197], v[166:169], v[100:103]
	v_mfma_f32_16x16x32_bf16 v[96:99], v[202:205], v[166:169], v[96:99]
	v_mfma_f32_16x16x32_bf16 v[84:87], v[194:197], v[178:181], v[84:87]
	v_mfma_f32_16x16x32_bf16 v[80:83], v[202:205], v[178:181], v[80:83]
	v_mfma_f32_16x16x32_bf16 v[68:71], v[194:197], v[186:189], v[68:71]
	v_mfma_f32_16x16x32_bf16 v[64:67], v[202:205], v[186:189], v[64:67]
	v_mfma_f32_16x16x32_bf16 v[116:119], v[198:201], v[148:151], v[116:119]
	v_mfma_f32_16x16x32_bf16 v[112:115], v[206:209], v[148:151], v[112:115]
	v_mfma_f32_16x16x32_bf16 v[100:103], v[198:201], v[174:177], v[100:103]
	v_mfma_f32_16x16x32_bf16 v[96:99], v[206:209], v[174:177], v[96:99]
	v_mfma_f32_16x16x32_bf16 v[84:87], v[198:201], v[182:185], v[84:87]
	v_mfma_f32_16x16x32_bf16 v[80:83], v[206:209], v[182:185], v[80:83]
	v_mfma_f32_16x16x32_bf16 v[68:71], v[198:201], v[190:193], v[68:71]
	s_setprio 0
	v_mfma_f32_16x16x32_bf16 v[64:67], v[206:209], v[190:193], v[64:67]
	s_barrier
	s_mov_b32 m0, s39
	v_lshl_add_u64 v[210:211], s[14:15], 0, v[156:157]
	global_load_lds_dwordx4 v[210:211], off
	s_add_i32 m0, s39, 0x2000
	v_lshl_add_u64 v[210:211], s[14:15], 0, v[158:159]
	global_load_lds_dwordx4 v[210:211], off
	s_mov_b32 m0, s25
	v_lshl_add_u64 v[210:211], s[18:19], 0, v[156:157]
	global_load_lds_dwordx4 v[210:211], off
	s_mov_b32 m0, s26
	v_lshl_add_u64 v[210:211], s[18:19], 0, v[158:159]
	global_load_lds_dwordx4 v[210:211], off
	s_add_u32 s40, s14, 0x80000
	s_addc_u32 s41, s15, 0
	s_add_i32 s39, s42, s23
	s_mov_b32 m0, s39
	v_lshl_add_u64 v[210:211], s[40:41], 0, v[156:157]
	global_load_lds_dwordx4 v[210:211], off
	s_add_i32 m0, s39, 0x2000
	v_lshl_add_u64 v[210:211], s[40:41], 0, v[158:159]
	global_load_lds_dwordx4 v[210:211], off
	ds_read_b128 v[144:147], v172 offset:16384
	ds_read_b128 v[166:169], v172 offset:18432
	ds_read_b128 v[178:181], v172 offset:20480
	ds_read_b128 v[186:189], v172 offset:22528
	ds_read_b128 v[148:151], v172 offset:17408
	ds_read_b128 v[174:177], v172 offset:19456
	ds_read_b128 v[182:185], v172 offset:21504
	ds_read_b128 v[190:193], v172 offset:23552
	s_waitcnt vmcnt(8)
	s_waitcnt lgkmcnt(0)
	s_barrier
	v_mfma_f32_16x16x32_bf16 v[60:63], v[128:131], v[144:147], v[60:63]
	s_setprio 1
	v_mfma_f32_16x16x32_bf16 v[56:59], v[136:139], v[144:147], v[56:59]
	v_mfma_f32_16x16x32_bf16 v[44:47], v[128:131], v[166:169], v[44:47]
	v_mfma_f32_16x16x32_bf16 v[40:43], v[136:139], v[166:169], v[40:43]
	v_mfma_f32_16x16x32_bf16 v[28:31], v[128:131], v[178:181], v[28:31]
	v_mfma_f32_16x16x32_bf16 v[24:27], v[136:139], v[178:181], v[24:27]
	v_mfma_f32_16x16x32_bf16 v[12:15], v[128:131], v[186:189], v[12:15]
	v_mfma_f32_16x16x32_bf16 v[8:11], v[136:139], v[186:189], v[8:11]
	v_mfma_f32_16x16x32_bf16 v[60:63], v[132:135], v[148:151], v[60:63]
	v_mfma_f32_16x16x32_bf16 v[56:59], v[140:143], v[148:151], v[56:59]
	v_mfma_f32_16x16x32_bf16 v[44:47], v[132:135], v[174:177], v[44:47]
	v_mfma_f32_16x16x32_bf16 v[40:43], v[140:143], v[174:177], v[40:43]
	v_mfma_f32_16x16x32_bf16 v[28:31], v[132:135], v[182:185], v[28:31]
	v_mfma_f32_16x16x32_bf16 v[24:27], v[140:143], v[182:185], v[24:27]
	v_mfma_f32_16x16x32_bf16 v[12:15], v[132:135], v[190:193], v[12:15]
	v_mfma_f32_16x16x32_bf16 v[8:11], v[140:143], v[190:193], v[8:11]
	v_mfma_f32_16x16x32_bf16 v[52:55], v[194:197], v[144:147], v[52:55]
	v_mfma_f32_16x16x32_bf16 v[48:51], v[202:205], v[144:147], v[48:51]
	s_add_i32 s39, 0, 0x18000
	v_add_u32_e32 v140, s39, v170
	v_mfma_f32_16x16x32_bf16 v[36:39], v[194:197], v[166:169], v[36:39]
	v_mfma_f32_16x16x32_bf16 v[32:35], v[202:205], v[166:169], v[32:35]
	v_mfma_f32_16x16x32_bf16 v[20:23], v[194:197], v[178:181], v[20:23]
	v_mfma_f32_16x16x32_bf16 v[16:19], v[202:205], v[178:181], v[16:19]
	v_mfma_f32_16x16x32_bf16 v[4:7], v[194:197], v[186:189], v[4:7]
	v_mfma_f32_16x16x32_bf16 v[0:3], v[202:205], v[186:189], v[0:3]
	v_mfma_f32_16x16x32_bf16 v[52:55], v[198:201], v[148:151], v[52:55]
	v_mfma_f32_16x16x32_bf16 v[48:51], v[206:209], v[148:151], v[48:51]
	v_mfma_f32_16x16x32_bf16 v[36:39], v[198:201], v[174:177], v[36:39]
	v_mfma_f32_16x16x32_bf16 v[32:35], v[206:209], v[174:177], v[32:35]
	v_mfma_f32_16x16x32_bf16 v[20:23], v[198:201], v[182:185], v[20:23]
	v_mfma_f32_16x16x32_bf16 v[16:19], v[206:209], v[182:185], v[16:19]
	v_mfma_f32_16x16x32_bf16 v[4:7], v[198:201], v[190:193], v[4:7]
	s_setprio 0
	v_mfma_f32_16x16x32_bf16 v[0:3], v[206:209], v[190:193], v[0:3]
	s_barrier
; #define PG8_STAGE(bufoff, gbase, voff) do { _Pragma("unroll") for (int _i = 0; _i < 2; ++_i) \
;         __builtin_amdgcn_global_load_lds((const unsigned*)((const char*)(gbase) + (voff)[_i]), (LAS unsigned*)(lds + (bufoff) + ldsw + _i * 8192), 16, 0, 0); } while (0)
; #define PG8_LDA(dst, b, h) do { _Pragma("unroll") for (int m = 0; m < 4; ++m) _Pragma("unroll") for (int k = 0; k < 2; ++k) dst[m][k] = *(const LAS bf16x8*)(lds + PG8_SA(b, h) + aoff + m * 2048 + k * 1024); } while (0)
; #define PG8_LDB(dst, b, h) do { _Pragma("unroll") for (int n = 0; n < 2; ++n) _Pragma("unroll") for (int k = 0; k < 2; ++k) dst[n][k] = *(const LAS bf16x8*)(lds + PG8_SB(b, h) + boff + n * 2048 + k * 1024); } while (0)
; #define PG8_WAIT_V(n) asm volatile("s_waitcnt vmcnt(" #n ")" ::: "memory")
; #define PG8_WAIT_L(n) asm volatile("s_waitcnt lgkmcnt(" #n ")" ::: "memory")
; #define PG8_BAR __builtin_amdgcn_s_barrier()
; #define PG8_SCHED __builtin_amdgcn_sched_barrier(0)
; template <class Epi>
; __device__ __forceinline__ void gemm_phase(LAS unsigned char* lds, const Gemm g, const StaticOrder& S, const Epi& E) {
;     ...
;             PG8_LDB(B0, 0, 0); PG8_SCHED; PG8_LDA(At, 0, 0); PG8_STAGE(PG8_SA(1, 1), a1 + hstepA, voffA);
;             PG8_WAIT_L(8); PG8_BAR; PG8_WAIT_L(0); PG8_MMA(0, 0, At, B0); PG8_BAR; PG8_SCHED;
;             PG8_LDB(B1, 0, 1); PG8_STAGE(PG8_SB(0, 0), b2, voffB);
;             PG8_BAR; PG8_WAIT_L(0); PG8_MMA(0, 1, At, B1); PG8_BAR;
;             PG8_LDA(At, 0, 1); PG8_STAGE(PG8_SA(0, 0), a2, voffA);
;             PG8_BAR; PG8_WAIT_L(0); PG8_MMA(1, 0, At, B0); PG8_BAR; PG8_SCHED;
;             PG8_STAGE(PG8_SB(0, 1), b2 + hstepB, voffB);
;             PG8_WAIT_V(6); PG8_BAR; PG8_MMA(1, 1, At, B1); PG8_BAR;
;             PG8_LDB(B0, 1, 0); PG8_SCHED; PG8_LDA(At, 1, 0); PG8_STAGE(PG8_SA(0, 1), a2 + hstepA, voffA);
;             PG8_WAIT_L(8); PG8_BAR; PG8_WAIT_L(0); PG8_MMA(0, 0, At, B0); PG8_BAR; PG8_SCHED;
;             PG8_LDB(B1, 1, 1); PG8_STAGE(PG8_SB(1, 0), b3, voffB);
;             PG8_BAR; PG8_WAIT_L(0); PG8_MMA(0, 1, At, B1); PG8_BAR;
;             PG8_LDA(At, 1, 1); PG8_STAGE(PG8_SA(1, 0), a3, voffA);
;             PG8_BAR; PG8_WAIT_L(0); PG8_MMA(1, 0, At, B0); PG8_BAR; PG8_SCHED;
;             PG8_STAGE(PG8_SB(1, 1), b3 + hstepB, voffB);
;             PG8_WAIT_V(6); PG8_BAR; PG8_MMA(1, 1, At, B1); PG8_BAR;
	s_add_u32 s18, s18, 0x80000
	s_addc_u32 s19, s19, 0
	s_mov_b32 m0, s27
	v_lshl_add_u64 v[194:195], s[18:19], 0, v[156:157]
	global_load_lds_dwordx4 v[194:195], off
	s_mov_b32 m0, s28
	v_lshl_add_u64 v[194:195], s[18:19], 0, v[158:159]
	global_load_lds_dwordx4 v[194:195], off
	ds_read_b128 v[128:131], v140
	ds_read_b128 v[136:139], v140 offset:2048
	ds_read_b128 v[132:135], v140 offset:1024
	ds_read_b128 v[140:143], v140 offset:3072
	ds_read_b128 v[144:147], v172 offset:32768
	ds_read_b128 v[166:169], v172 offset:34816
	ds_read_b128 v[178:181], v172 offset:36864
	ds_read_b128 v[186:189], v172 offset:38912
	ds_read_b128 v[148:151], v172 offset:33792
	ds_read_b128 v[174:177], v172 offset:35840
	ds_read_b128 v[182:185], v172 offset:37888
	ds_read_b128 v[190:193], v172 offset:39936
	s_mov_b32 s40, 0x1c000
	s_add_u32 s18, s14, 0x4000
	s_addc_u32 s19, s15, 0
	s_add_i32 s39, s39, s23
	v_add_u32_e32 v152, s40, v170
	ds_read_b128 v[194:197], v152
	ds_read_b128 v[202:205], v152 offset:2048
	ds_read_b128 v[198:201], v152 offset:1024
	ds_read_b128 v[206:209], v152 offset:3072
	s_waitcnt vmcnt(8)
	s_waitcnt lgkmcnt(0)
	s_barrier
	v_mfma_f32_16x16x32_bf16 v[124:127], v[128:131], v[144:147], v[124:127]
	s_setprio 1
	v_mfma_f32_16x16x32_bf16 v[120:123], v[136:139], v[144:147], v[120:123]
	v_mfma_f32_16x16x32_bf16 v[108:111], v[128:131], v[166:169], v[108:111]
	v_mfma_f32_16x16x32_bf16 v[104:107], v[136:139], v[166:169], v[104:107]
	v_mfma_f32_16x16x32_bf16 v[92:95], v[128:131], v[178:181], v[92:95]
	v_mfma_f32_16x16x32_bf16 v[88:91], v[136:139], v[178:181], v[88:91]
	v_mfma_f32_16x16x32_bf16 v[76:79], v[128:131], v[186:189], v[76:79]
	v_mfma_f32_16x16x32_bf16 v[72:75], v[136:139], v[186:189], v[72:75]
	v_mfma_f32_16x16x32_bf16 v[124:127], v[132:135], v[148:151], v[124:127]
	v_mfma_f32_16x16x32_bf16 v[120:123], v[140:143], v[148:151], v[120:123]
	v_mfma_f32_16x16x32_bf16 v[108:111], v[132:135], v[174:177], v[108:111]
	v_mfma_f32_16x16x32_bf16 v[104:107], v[140:143], v[174:177], v[104:107]
	v_mfma_f32_16x16x32_bf16 v[92:95], v[132:135], v[182:185], v[92:95]
	v_mfma_f32_16x16x32_bf16 v[88:91], v[140:143], v[182:185], v[88:91]
	v_mfma_f32_16x16x32_bf16 v[76:79], v[132:135], v[190:193], v[76:79]
	v_mfma_f32_16x16x32_bf16 v[72:75], v[140:143], v[190:193], v[72:75]
	v_mfma_f32_16x16x32_bf16 v[116:119], v[194:197], v[144:147], v[116:119]
	v_mfma_f32_16x16x32_bf16 v[112:115], v[202:205], v[144:147], v[112:115]
	v_mfma_f32_16x16x32_bf16 v[100:103], v[194:197], v[166:169], v[100:103]
	v_mfma_f32_16x16x32_bf16 v[96:99], v[202:205], v[166:169], v[96:99]
	v_mfma_f32_16x16x32_bf16 v[84:87], v[194:197], v[178:181], v[84:87]
	v_mfma_f32_16x16x32_bf16 v[80:83], v[202:205], v[178:181], v[80:83]
	v_mfma_f32_16x16x32_bf16 v[68:71], v[194:197], v[186:189], v[68:71]
	v_mfma_f32_16x16x32_bf16 v[64:67], v[202:205], v[186:189], v[64:67]
	v_mfma_f32_16x16x32_bf16 v[116:119], v[198:201], v[148:151], v[116:119]
	v_mfma_f32_16x16x32_bf16 v[112:115], v[206:209], v[148:151], v[112:115]
	v_mfma_f32_16x16x32_bf16 v[100:103], v[198:201], v[174:177], v[100:103]
	v_mfma_f32_16x16x32_bf16 v[96:99], v[206:209], v[174:177], v[96:99]
	v_mfma_f32_16x16x32_bf16 v[84:87], v[198:201], v[182:185], v[84:87]
	v_mfma_f32_16x16x32_bf16 v[80:83], v[206:209], v[182:185], v[80:83]
	v_mfma_f32_16x16x32_bf16 v[68:71], v[198:201], v[190:193], v[68:71]
	s_setprio 0
	v_mfma_f32_16x16x32_bf16 v[64:67], v[206:209], v[190:193], v[64:67]
	s_barrier
	s_mov_b32 m0, s39
	v_lshl_add_u64 v[210:211], s[18:19], 0, v[156:157]
	global_load_lds_dwordx4 v[210:211], off
	s_add_i32 m0, s39, 0x2000
	v_lshl_add_u64 v[210:211], s[18:19], 0, v[158:159]
	global_load_lds_dwordx4 v[210:211], off
	s_mov_b32 m0, s29
	v_lshl_add_u64 v[210:211], s[16:17], 0, v[156:157]
	global_load_lds_dwordx4 v[210:211], off
	s_mov_b32 m0, s30
	v_lshl_add_u64 v[210:211], s[16:17], 0, v[158:159]
	global_load_lds_dwordx4 v[210:211], off
	s_add_u32 s14, s14, 0x84000
	s_addc_u32 s15, s15, 0
	s_add_i32 s16, s40, s23
	s_mov_b32 m0, s16
	v_lshl_add_u64 v[210:211], s[14:15], 0, v[156:157]
	global_load_lds_dwordx4 v[210:211], off
	s_add_i32 m0, s16, 0x2000
	v_lshl_add_u64 v[210:211], s[14:15], 0, v[158:159]
	global_load_lds_dwordx4 v[210:211], off
	ds_read_b128 v[144:147], v172 offset:49152
	ds_read_b128 v[166:169], v172 offset:51200
	ds_read_b128 v[178:181], v172 offset:53248
	ds_read_b128 v[186:189], v172 offset:55296
	ds_read_b128 v[148:151], v172 offset:50176
	ds_read_b128 v[174:177], v172 offset:52224
	ds_read_b128 v[182:185], v172 offset:54272
	ds_read_b128 v[190:193], v172 offset:56320
	s_waitcnt vmcnt(8)
	s_waitcnt lgkmcnt(0)
	s_barrier
	v_mfma_f32_16x16x32_bf16 v[60:63], v[128:131], v[144:147], v[60:63]
	s_setprio 1
	v_mfma_f32_16x16x32_bf16 v[56:59], v[136:139], v[144:147], v[56:59]
	v_mfma_f32_16x16x32_bf16 v[44:47], v[128:131], v[166:169], v[44:47]
	v_mfma_f32_16x16x32_bf16 v[40:43], v[136:139], v[166:169], v[40:43]
	v_mfma_f32_16x16x32_bf16 v[28:31], v[128:131], v[178:181], v[28:31]
	v_mfma_f32_16x16x32_bf16 v[24:27], v[136:139], v[178:181], v[24:27]
	v_mfma_f32_16x16x32_bf16 v[12:15], v[128:131], v[186:189], v[12:15]
	v_mfma_f32_16x16x32_bf16 v[8:11], v[136:139], v[186:189], v[8:11]
	v_mfma_f32_16x16x32_bf16 v[60:63], v[132:135], v[148:151], v[60:63]
	v_mfma_f32_16x16x32_bf16 v[56:59], v[140:143], v[148:151], v[56:59]
	v_mfma_f32_16x16x32_bf16 v[44:47], v[132:135], v[174:177], v[44:47]
	v_mfma_f32_16x16x32_bf16 v[40:43], v[140:143], v[174:177], v[40:43]
	v_mfma_f32_16x16x32_bf16 v[28:31], v[132:135], v[182:185], v[28:31]
	v_mfma_f32_16x16x32_bf16 v[24:27], v[140:143], v[182:185], v[24:27]
	v_mfma_f32_16x16x32_bf16 v[12:15], v[132:135], v[190:193], v[12:15]
	v_mfma_f32_16x16x32_bf16 v[8:11], v[140:143], v[190:193], v[8:11]
	v_mfma_f32_16x16x32_bf16 v[52:55], v[194:197], v[144:147], v[52:55]
	v_mfma_f32_16x16x32_bf16 v[48:51], v[202:205], v[144:147], v[48:51]
	s_add_i32 s38, s38, 2
	s_add_u32 s12, s12, 0x8000
	s_addc_u32 s13, s13, 0
	s_add_u32 s36, s36, 0x8000
	s_addc_u32 s37, s37, 0
	v_mfma_f32_16x16x32_bf16 v[36:39], v[194:197], v[166:169], v[36:39]
	v_mfma_f32_16x16x32_bf16 v[32:35], v[202:205], v[166:169], v[32:35]
	v_mfma_f32_16x16x32_bf16 v[20:23], v[194:197], v[178:181], v[20:23]
	v_mfma_f32_16x16x32_bf16 v[16:19], v[202:205], v[178:181], v[16:19]
	v_mfma_f32_16x16x32_bf16 v[4:7], v[194:197], v[186:189], v[4:7]
	v_mfma_f32_16x16x32_bf16 v[0:3], v[202:205], v[186:189], v[0:3]
	v_mfma_f32_16x16x32_bf16 v[52:55], v[198:201], v[148:151], v[52:55]
	v_mfma_f32_16x16x32_bf16 v[48:51], v[206:209], v[148:151], v[48:51]
	v_mfma_f32_16x16x32_bf16 v[36:39], v[198:201], v[174:177], v[36:39]
	v_mfma_f32_16x16x32_bf16 v[32:35], v[206:209], v[174:177], v[32:35]
	v_mfma_f32_16x16x32_bf16 v[20:23], v[198:201], v[182:185], v[20:23]
	v_mfma_f32_16x16x32_bf16 v[16:19], v[206:209], v[182:185], v[16:19]
	v_mfma_f32_16x16x32_bf16 v[4:7], v[198:201], v[190:193], v[4:7]
	s_cmp_gt_u32 s38, 29
	s_setprio 0
	v_mfma_f32_16x16x32_bf16 v[0:3], v[206:209], v[190:193], v[0:3]
	s_barrier
	s_cbranch_scc0 .LBB0_247
